# GEMM K-loops (UP, DN/OUT, MRG): the s_setprio 0 / s_setprio 1 pair between the two MFMA blocks of a super-phase removed
# speedup vs baseline: 1.0105x; 1.0105x over previous
.LBB0_44:
	s_add_u32 s46, s42, s44
	s_addc_u32 s47, s43, s45
	s_add_u32 s46, s46, 0x100
	s_addc_u32 s47, s47, 0
	s_add_u32 s57, s54, s44
	s_addc_u32 s58, s55, s45
	s_cmpk_eq_i32 s44, 0x700
	s_cselect_b32 s49, s31, s47
	s_cselect_b32 s48, s51, s46
	s_cselect_b32 s47, s52, s58
	s_cselect_b32 s46, s53, s57
	s_add_i32 s57, 0, 0x10000
	v_add_u32_e32 v0, s57, v233
	s_add_i32 s60, 0, 0x14000
	ds_read_b128 v[134:137], v0
	ds_read_b128 v[138:141], v0 offset:1024
	ds_read_b128 v[142:145], v0 offset:2048
	ds_read_b128 v[146:149], v0 offset:3072
	v_add_u32_e32 v0, s60, v233
	ds_read_b128 v[150:153], v0
	ds_read_b128 v[154:157], v0 offset:1024
	ds_read_b128 v[158:161], v0 offset:2048
	ds_read_b128 v[162:165], v0 offset:3072
	v_lshl_add_u64 v[202:203], v[216:217], 0, s[44:45]
	s_add_i32 m0, s8, 0xc000
	ds_read_b128 v[166:169], v235
	ds_read_b128 v[170:173], v235 offset:1024
	ds_read_b128 v[174:177], v235 offset:2048
	ds_read_b128 v[178:181], v235 offset:3072
	ds_read_b128 v[182:185], v235 offset:4096
	ds_read_b128 v[186:189], v235 offset:5120
	ds_read_b128 v[190:193], v235 offset:6144
	ds_read_b128 v[194:197], v235 offset:7168
	global_load_lds_dwordx4 v[202:203], off
	v_lshl_add_u64 v[202:203], v[218:219], 0, s[44:45]
	s_add_i32 m0, s8, 0xe000
	s_nop 0
	global_load_lds_dwordx4 v[202:203], off
	s_waitcnt vmcnt(8)
	s_waitcnt lgkmcnt(0)
	s_barrier
	s_setprio 1
	s_waitcnt lgkmcnt(0)
	v_mfma_f32_16x16x32_bf16 v[130:133], v[134:137], v[166:169], v[130:133]
	v_mfma_f32_16x16x32_bf16 v[126:129], v[142:145], v[166:169], v[126:129]
	v_mfma_f32_16x16x32_bf16 v[114:117], v[134:137], v[174:177], v[114:117]
	v_mfma_f32_16x16x32_bf16 v[110:113], v[142:145], v[174:177], v[110:113]
	v_mfma_f32_16x16x32_bf16 v[98:101], v[134:137], v[182:185], v[98:101]
	v_mfma_f32_16x16x32_bf16 v[90:93], v[142:145], v[182:185], v[90:93]
	v_mfma_f32_16x16x32_bf16 v[78:81], v[134:137], v[190:193], v[78:81]
	v_mfma_f32_16x16x32_bf16 v[74:77], v[142:145], v[190:193], v[74:77]
	v_mfma_f32_16x16x32_bf16 v[130:133], v[138:141], v[170:173], v[130:133]
	v_mfma_f32_16x16x32_bf16 v[126:129], v[146:149], v[170:173], v[126:129]
	v_mfma_f32_16x16x32_bf16 v[114:117], v[138:141], v[178:181], v[114:117]
	v_mfma_f32_16x16x32_bf16 v[110:113], v[146:149], v[178:181], v[110:113]
	v_mfma_f32_16x16x32_bf16 v[98:101], v[138:141], v[186:189], v[98:101]
	v_mfma_f32_16x16x32_bf16 v[90:93], v[146:149], v[186:189], v[90:93]
	v_mfma_f32_16x16x32_bf16 v[78:81], v[138:141], v[194:197], v[78:81]
	v_mfma_f32_16x16x32_bf16 v[74:77], v[146:149], v[194:197], v[74:77]
	v_mfma_f32_16x16x32_bf16 v[122:125], v[150:153], v[166:169], v[122:125]
	v_mfma_f32_16x16x32_bf16 v[118:121], v[158:161], v[166:169], v[118:121]
	v_mfma_f32_16x16x32_bf16 v[106:109], v[150:153], v[174:177], v[106:109]
	v_mfma_f32_16x16x32_bf16 v[102:105], v[158:161], v[174:177], v[102:105]
	v_mfma_f32_16x16x32_bf16 v[86:89], v[150:153], v[182:185], v[86:89]
	v_mfma_f32_16x16x32_bf16 v[82:85], v[158:161], v[182:185], v[82:85]
	v_mfma_f32_16x16x32_bf16 v[70:73], v[150:153], v[190:193], v[70:73]
	v_mfma_f32_16x16x32_bf16 v[66:69], v[158:161], v[190:193], v[66:69]
	v_mfma_f32_16x16x32_bf16 v[122:125], v[154:157], v[170:173], v[122:125]
	v_mfma_f32_16x16x32_bf16 v[118:121], v[162:165], v[170:173], v[118:121]
	v_mfma_f32_16x16x32_bf16 v[106:109], v[154:157], v[178:181], v[106:109]
	v_mfma_f32_16x16x32_bf16 v[102:105], v[162:165], v[178:181], v[102:105]
	v_mfma_f32_16x16x32_bf16 v[86:89], v[154:157], v[186:189], v[86:89]
	v_mfma_f32_16x16x32_bf16 v[82:85], v[162:165], v[186:189], v[82:85]
	v_mfma_f32_16x16x32_bf16 v[70:73], v[154:157], v[194:197], v[70:73]
	v_mfma_f32_16x16x32_bf16 v[66:69], v[162:165], v[194:197], v[66:69]
	s_setprio 0
	s_barrier
	s_add_i32 s57, s57, s6
	v_lshl_add_u64 v[202:203], s[46:47], 0, v[208:209]
	s_mov_b32 m0, s57
	ds_read_b128 v[166:169], v235 offset:16384
	ds_read_b128 v[170:173], v235 offset:17408
	ds_read_b128 v[174:177], v235 offset:18432
	ds_read_b128 v[178:181], v235 offset:19456
	ds_read_b128 v[182:185], v235 offset:20480
	ds_read_b128 v[186:189], v235 offset:21504
	ds_read_b128 v[190:193], v235 offset:22528
	ds_read_b128 v[194:197], v235 offset:23552
	global_load_lds_dwordx4 v[202:203], off
	s_add_i32 m0, s57, 0x2000
	s_add_u32 s58, s46, 0x40000
	v_lshl_add_u64 v[220:221], s[46:47], 0, v[94:95]
	s_addc_u32 s59, s47, 0
	s_add_i32 s57, s60, s6
	global_load_lds_dwordx4 v[220:221], off
	v_lshl_add_u64 v[236:237], s[58:59], 0, v[208:209]
	s_mov_b32 m0, s57
	v_lshl_add_u64 v[238:239], s[48:49], 0, v[94:95]
	global_load_lds_dwordx4 v[236:237], off
	v_lshl_add_u64 v[236:237], s[58:59], 0, v[94:95]
	s_add_i32 m0, s57, 0x2000
	s_nop 0
	global_load_lds_dwordx4 v[236:237], off
	v_lshl_add_u64 v[236:237], s[48:49], 0, v[208:209]
	s_mov_b32 m0, s8
	s_nop 0
	global_load_lds_dwordx4 v[236:237], off
	s_mov_b32 m0, s9
	s_nop 0
	global_load_lds_dwordx4 v[238:239], off
	s_waitcnt vmcnt(8)
	s_waitcnt lgkmcnt(0)
	s_barrier
	s_setprio 1
	s_waitcnt lgkmcnt(0)
	v_mfma_f32_16x16x32_bf16 v[62:65], v[134:137], v[166:169], v[62:65]
	v_mfma_f32_16x16x32_bf16 v[58:61], v[142:145], v[166:169], v[58:61]
	v_mfma_f32_16x16x32_bf16 v[46:49], v[134:137], v[174:177], v[46:49]
	v_mfma_f32_16x16x32_bf16 v[42:45], v[142:145], v[174:177], v[42:45]
	v_mfma_f32_16x16x32_bf16 v[30:33], v[134:137], v[182:185], v[30:33]
	v_mfma_f32_16x16x32_bf16 v[26:29], v[142:145], v[182:185], v[26:29]
	v_mfma_f32_16x16x32_bf16 v[14:17], v[134:137], v[190:193], v[14:17]
	v_mfma_f32_16x16x32_bf16 v[10:13], v[142:145], v[190:193], v[10:13]
	v_mfma_f32_16x16x32_bf16 v[62:65], v[138:141], v[170:173], v[62:65]
	v_mfma_f32_16x16x32_bf16 v[58:61], v[146:149], v[170:173], v[58:61]
	v_mfma_f32_16x16x32_bf16 v[46:49], v[138:141], v[178:181], v[46:49]
	v_mfma_f32_16x16x32_bf16 v[42:45], v[146:149], v[178:181], v[42:45]
	v_mfma_f32_16x16x32_bf16 v[30:33], v[138:141], v[186:189], v[30:33]
	v_mfma_f32_16x16x32_bf16 v[26:29], v[146:149], v[186:189], v[26:29]
	v_mfma_f32_16x16x32_bf16 v[14:17], v[138:141], v[194:197], v[14:17]
	v_mfma_f32_16x16x32_bf16 v[10:13], v[146:149], v[194:197], v[10:13]
	v_mfma_f32_16x16x32_bf16 v[54:57], v[150:153], v[166:169], v[54:57]
	v_mfma_f32_16x16x32_bf16 v[50:53], v[158:161], v[166:169], v[50:53]
	v_mfma_f32_16x16x32_bf16 v[38:41], v[150:153], v[174:177], v[38:41]
	v_mfma_f32_16x16x32_bf16 v[34:37], v[158:161], v[174:177], v[34:37]
	v_mfma_f32_16x16x32_bf16 v[22:25], v[150:153], v[182:185], v[22:25]
	v_mfma_f32_16x16x32_bf16 v[18:21], v[158:161], v[182:185], v[18:21]
	v_mfma_f32_16x16x32_bf16 v[6:9], v[150:153], v[190:193], v[6:9]
	v_mfma_f32_16x16x32_bf16 v[2:5], v[158:161], v[190:193], v[2:5]
	v_mfma_f32_16x16x32_bf16 v[54:57], v[154:157], v[170:173], v[54:57]
	v_mfma_f32_16x16x32_bf16 v[50:53], v[162:165], v[170:173], v[50:53]
	v_mfma_f32_16x16x32_bf16 v[38:41], v[154:157], v[178:181], v[38:41]
	v_mfma_f32_16x16x32_bf16 v[34:37], v[162:165], v[178:181], v[34:37]
	v_mfma_f32_16x16x32_bf16 v[22:25], v[154:157], v[186:189], v[22:25]
	v_mfma_f32_16x16x32_bf16 v[18:21], v[162:165], v[186:189], v[18:21]
	v_mfma_f32_16x16x32_bf16 v[6:9], v[154:157], v[194:197], v[6:9]
	v_mfma_f32_16x16x32_bf16 v[2:5], v[162:165], v[194:197], v[2:5]
	s_setprio 0
	s_barrier
	s_add_i32 s57, 0, 0x18000
	v_add_u32_e32 v0, s57, v233
	s_add_i32 s58, 0, 0x1c000
	ds_read_b128 v[134:137], v0
	ds_read_b128 v[138:141], v0 offset:1024
	ds_read_b128 v[142:145], v0 offset:2048
	ds_read_b128 v[146:149], v0 offset:3072
	v_add_u32_e32 v0, s58, v233
	ds_read_b128 v[150:153], v0
	ds_read_b128 v[154:157], v0 offset:1024
	ds_read_b128 v[158:161], v0 offset:2048
	ds_read_b128 v[162:165], v0 offset:3072
	s_add_u32 s48, s48, 0x40000
	s_addc_u32 s49, s49, 0
	s_mov_b32 m0, s12
	v_lshl_add_u64 v[240:241], s[48:49], 0, v[208:209]
	ds_read_b128 v[166:169], v235 offset:32768
	ds_read_b128 v[170:173], v235 offset:33792
	ds_read_b128 v[174:177], v235 offset:34816
	ds_read_b128 v[178:181], v235 offset:35840
	ds_read_b128 v[182:185], v235 offset:36864
	ds_read_b128 v[186:189], v235 offset:37888
	ds_read_b128 v[190:193], v235 offset:38912
	ds_read_b128 v[194:197], v235 offset:39936
	global_load_lds_dwordx4 v[240:241], off
	v_lshl_add_u64 v[240:241], s[48:49], 0, v[94:95]
	s_mov_b32 m0, s13
	s_nop 0
	global_load_lds_dwordx4 v[240:241], off
	s_waitcnt vmcnt(8)
	s_waitcnt lgkmcnt(0)
	s_barrier
	s_setprio 1
	s_waitcnt lgkmcnt(0)
	v_mfma_f32_16x16x32_bf16 v[130:133], v[134:137], v[166:169], v[130:133]
	v_mfma_f32_16x16x32_bf16 v[126:129], v[142:145], v[166:169], v[126:129]
	v_mfma_f32_16x16x32_bf16 v[114:117], v[134:137], v[174:177], v[114:117]
	v_mfma_f32_16x16x32_bf16 v[110:113], v[142:145], v[174:177], v[110:113]
	v_mfma_f32_16x16x32_bf16 v[98:101], v[134:137], v[182:185], v[98:101]
	v_mfma_f32_16x16x32_bf16 v[90:93], v[142:145], v[182:185], v[90:93]
	v_mfma_f32_16x16x32_bf16 v[78:81], v[134:137], v[190:193], v[78:81]
	v_mfma_f32_16x16x32_bf16 v[74:77], v[142:145], v[190:193], v[74:77]
	v_mfma_f32_16x16x32_bf16 v[130:133], v[138:141], v[170:173], v[130:133]
	v_mfma_f32_16x16x32_bf16 v[126:129], v[146:149], v[170:173], v[126:129]
	v_mfma_f32_16x16x32_bf16 v[114:117], v[138:141], v[178:181], v[114:117]
	v_mfma_f32_16x16x32_bf16 v[110:113], v[146:149], v[178:181], v[110:113]
	v_mfma_f32_16x16x32_bf16 v[98:101], v[138:141], v[186:189], v[98:101]
	v_mfma_f32_16x16x32_bf16 v[90:93], v[146:149], v[186:189], v[90:93]
	v_mfma_f32_16x16x32_bf16 v[78:81], v[138:141], v[194:197], v[78:81]
	v_mfma_f32_16x16x32_bf16 v[74:77], v[146:149], v[194:197], v[74:77]
	v_mfma_f32_16x16x32_bf16 v[122:125], v[150:153], v[166:169], v[122:125]
	v_mfma_f32_16x16x32_bf16 v[118:121], v[158:161], v[166:169], v[118:121]
	v_mfma_f32_16x16x32_bf16 v[106:109], v[150:153], v[174:177], v[106:109]
	v_mfma_f32_16x16x32_bf16 v[102:105], v[158:161], v[174:177], v[102:105]
	v_mfma_f32_16x16x32_bf16 v[86:89], v[150:153], v[182:185], v[86:89]
	v_mfma_f32_16x16x32_bf16 v[82:85], v[158:161], v[182:185], v[82:85]
	v_mfma_f32_16x16x32_bf16 v[70:73], v[150:153], v[190:193], v[70:73]
	v_mfma_f32_16x16x32_bf16 v[66:69], v[158:161], v[190:193], v[66:69]
	v_mfma_f32_16x16x32_bf16 v[122:125], v[154:157], v[170:173], v[122:125]
	v_mfma_f32_16x16x32_bf16 v[118:121], v[162:165], v[170:173], v[118:121]
	v_mfma_f32_16x16x32_bf16 v[106:109], v[154:157], v[178:181], v[106:109]
	v_mfma_f32_16x16x32_bf16 v[102:105], v[162:165], v[178:181], v[102:105]
	v_mfma_f32_16x16x32_bf16 v[86:89], v[154:157], v[186:189], v[86:89]
	v_mfma_f32_16x16x32_bf16 v[82:85], v[162:165], v[186:189], v[82:85]
	v_mfma_f32_16x16x32_bf16 v[70:73], v[154:157], v[194:197], v[70:73]
	v_mfma_f32_16x16x32_bf16 v[66:69], v[162:165], v[194:197], v[66:69]
	s_setprio 0
	s_barrier
	s_add_i32 s48, s57, s6
	v_lshl_add_u64 v[202:203], v[202:203], 0, s[34:35]
	s_mov_b32 m0, s48
	ds_read_b128 v[166:169], v235 offset:49152
	ds_read_b128 v[170:173], v235 offset:50176
	ds_read_b128 v[174:177], v235 offset:51200
	ds_read_b128 v[178:181], v235 offset:52224
	ds_read_b128 v[182:185], v235 offset:53248
	ds_read_b128 v[186:189], v235 offset:54272
	ds_read_b128 v[190:193], v235 offset:55296
	ds_read_b128 v[194:197], v235 offset:56320
	global_load_lds_dwordx4 v[202:203], off
	s_add_i32 m0, s48, 0x2000
	s_add_u32 s46, s46, 0x40080
	v_lshl_add_u64 v[202:203], v[220:221], 0, s[34:35]
	s_addc_u32 s47, s47, 0
	s_add_i32 s48, s58, s6
	global_load_lds_dwordx4 v[202:203], off
	v_lshl_add_u64 v[202:203], s[46:47], 0, v[208:209]
	s_mov_b32 m0, s48
	s_nop 0
	global_load_lds_dwordx4 v[202:203], off
	v_lshl_add_u64 v[202:203], s[46:47], 0, v[94:95]
	s_add_i32 m0, s48, 0x2000
	s_nop 0
	global_load_lds_dwordx4 v[202:203], off
	v_lshl_add_u64 v[202:203], v[236:237], 0, s[34:35]
	s_mov_b32 m0, s28
	s_nop 0
	global_load_lds_dwordx4 v[202:203], off
	v_lshl_add_u64 v[202:203], v[238:239], 0, s[34:35]
	s_mov_b32 m0, s29
	s_nop 0
	global_load_lds_dwordx4 v[202:203], off
	s_waitcnt vmcnt(8)
	s_waitcnt lgkmcnt(0)
	s_barrier
	s_setprio 1
	s_waitcnt lgkmcnt(0)
	v_mfma_f32_16x16x32_bf16 v[62:65], v[134:137], v[166:169], v[62:65]
	v_mfma_f32_16x16x32_bf16 v[58:61], v[142:145], v[166:169], v[58:61]
	v_mfma_f32_16x16x32_bf16 v[46:49], v[134:137], v[174:177], v[46:49]
	v_mfma_f32_16x16x32_bf16 v[42:45], v[142:145], v[174:177], v[42:45]
	v_mfma_f32_16x16x32_bf16 v[30:33], v[134:137], v[182:185], v[30:33]
	v_mfma_f32_16x16x32_bf16 v[26:29], v[142:145], v[182:185], v[26:29]
	v_mfma_f32_16x16x32_bf16 v[14:17], v[134:137], v[190:193], v[14:17]
	v_mfma_f32_16x16x32_bf16 v[10:13], v[142:145], v[190:193], v[10:13]
	v_mfma_f32_16x16x32_bf16 v[62:65], v[138:141], v[170:173], v[62:65]
	v_mfma_f32_16x16x32_bf16 v[58:61], v[146:149], v[170:173], v[58:61]
	v_mfma_f32_16x16x32_bf16 v[46:49], v[138:141], v[178:181], v[46:49]
	v_mfma_f32_16x16x32_bf16 v[42:45], v[146:149], v[178:181], v[42:45]
	v_mfma_f32_16x16x32_bf16 v[30:33], v[138:141], v[186:189], v[30:33]
	v_mfma_f32_16x16x32_bf16 v[26:29], v[146:149], v[186:189], v[26:29]
	v_mfma_f32_16x16x32_bf16 v[14:17], v[138:141], v[194:197], v[14:17]
	v_mfma_f32_16x16x32_bf16 v[10:13], v[146:149], v[194:197], v[10:13]
	v_mfma_f32_16x16x32_bf16 v[54:57], v[150:153], v[166:169], v[54:57]
	v_mfma_f32_16x16x32_bf16 v[50:53], v[158:161], v[166:169], v[50:53]
	v_mfma_f32_16x16x32_bf16 v[38:41], v[150:153], v[174:177], v[38:41]
	v_mfma_f32_16x16x32_bf16 v[34:37], v[158:161], v[174:177], v[34:37]
	v_mfma_f32_16x16x32_bf16 v[22:25], v[150:153], v[182:185], v[22:25]
	v_mfma_f32_16x16x32_bf16 v[18:21], v[158:161], v[182:185], v[18:21]
	v_mfma_f32_16x16x32_bf16 v[6:9], v[150:153], v[190:193], v[6:9]
	v_mfma_f32_16x16x32_bf16 v[2:5], v[158:161], v[190:193], v[2:5]
	v_mfma_f32_16x16x32_bf16 v[54:57], v[154:157], v[170:173], v[54:57]
	v_mfma_f32_16x16x32_bf16 v[50:53], v[162:165], v[170:173], v[50:53]
	v_mfma_f32_16x16x32_bf16 v[38:41], v[154:157], v[178:181], v[38:41]
	v_mfma_f32_16x16x32_bf16 v[34:37], v[162:165], v[178:181], v[34:37]
	v_mfma_f32_16x16x32_bf16 v[22:25], v[154:157], v[186:189], v[22:25]
	v_mfma_f32_16x16x32_bf16 v[18:21], v[162:165], v[186:189], v[18:21]
	v_mfma_f32_16x16x32_bf16 v[6:9], v[154:157], v[194:197], v[6:9]
	v_mfma_f32_16x16x32_bf16 v[2:5], v[162:165], v[194:197], v[2:5]
	s_setprio 0
	s_barrier
	s_add_i32 s56, s56, 2
	s_add_u32 s44, s44, 0x100
	s_addc_u32 s45, s45, 0
	s_cmp_gt_u32 s56, 13
	s_cbranch_scc1 .LBB0_47

.LBB0_527:
	s_add_u32 s51, s22, 0x100
	s_addc_u32 s52, s23, 0
	s_add_u32 s22, s30, 0x80
	s_addc_u32 s23, s31, 0
	s_mov_b32 s30, 0
	s_waitcnt lgkmcnt(0)
	s_add_i32 s53, s30, 2
	s_add_u32 s54, s22, 0x80
	s_addc_u32 s31, s23, 0
	s_add_i32 s56, 0, 0x10000
	s_cmp_eq_u32 s46, s30
	s_cselect_b32 s31, s1, s31
	s_cselect_b32 s30, s0, s54
	s_cselect_b32 s55, s21, s52
	s_cselect_b32 s54, s20, s51
	s_add_i32 s57, 0, 0x14000
	v_add_u32_e32 v152, s56, v232
	v_add_u32_e32 v168, s57, v232
	ds_read_b128 v[140:143], v152
	ds_read_b128 v[144:147], v152 offset:1024
	ds_read_b128 v[148:151], v152 offset:2048
	ds_read_b128 v[152:155], v152 offset:3072
	ds_read_b128 v[156:159], v168
	ds_read_b128 v[160:163], v168 offset:1024
	ds_read_b128 v[164:167], v168 offset:2048
	ds_read_b128 v[168:171], v168 offset:3072
	s_add_i32 m0, s28, 0xc000
	ds_read_b128 v[172:175], v236
	ds_read_b128 v[176:179], v236 offset:1024
	ds_read_b128 v[180:183], v236 offset:2048
	ds_read_b128 v[184:187], v236 offset:3072
	ds_read_b128 v[188:191], v236 offset:4096
	ds_read_b128 v[192:195], v236 offset:5120
	ds_read_b128 v[208:211], v236 offset:6144
	ds_read_b128 v[212:215], v236 offset:7168
	global_load_lds_dwordx4 v138, s[22:23]
	s_add_i32 m0, s28, 0xe000
	s_nop 0
	global_load_lds_dwordx4 v136, s[22:23]
	s_waitcnt vmcnt(8)
	s_waitcnt lgkmcnt(0)
	s_barrier
	s_setprio 1
	s_waitcnt lgkmcnt(0)
	v_mfma_f32_16x16x32_bf16 v[130:133], v[140:143], v[172:175], 0
	v_mfma_f32_16x16x32_bf16 v[126:129], v[148:151], v[172:175], 0
	v_mfma_f32_16x16x32_bf16 v[114:117], v[140:143], v[180:183], 0
	v_mfma_f32_16x16x32_bf16 v[110:113], v[148:151], v[180:183], 0
	v_mfma_f32_16x16x32_bf16 v[98:101], v[140:143], v[188:191], 0
	v_mfma_f32_16x16x32_bf16 v[90:93], v[148:151], v[188:191], 0
	v_mfma_f32_16x16x32_bf16 v[78:81], v[140:143], v[208:211], 0
	v_mfma_f32_16x16x32_bf16 v[74:77], v[148:151], v[208:211], 0
	v_mfma_f32_16x16x32_bf16 v[130:133], v[144:147], v[176:179], v[130:133]
	v_mfma_f32_16x16x32_bf16 v[126:129], v[152:155], v[176:179], v[126:129]
	v_mfma_f32_16x16x32_bf16 v[114:117], v[144:147], v[184:187], v[114:117]
	v_mfma_f32_16x16x32_bf16 v[110:113], v[152:155], v[184:187], v[110:113]
	v_mfma_f32_16x16x32_bf16 v[98:101], v[144:147], v[192:195], v[98:101]
	v_mfma_f32_16x16x32_bf16 v[90:93], v[152:155], v[192:195], v[90:93]
	v_mfma_f32_16x16x32_bf16 v[78:81], v[144:147], v[212:215], v[78:81]
	v_mfma_f32_16x16x32_bf16 v[74:77], v[152:155], v[212:215], v[74:77]
	v_mfma_f32_16x16x32_bf16 v[122:125], v[156:159], v[172:175], 0
	v_mfma_f32_16x16x32_bf16 v[118:121], v[164:167], v[172:175], 0
	v_mfma_f32_16x16x32_bf16 v[106:109], v[156:159], v[180:183], 0
	v_mfma_f32_16x16x32_bf16 v[102:105], v[164:167], v[180:183], 0
	v_mfma_f32_16x16x32_bf16 v[86:89], v[156:159], v[188:191], 0
	v_mfma_f32_16x16x32_bf16 v[82:85], v[164:167], v[188:191], 0
	v_mfma_f32_16x16x32_bf16 v[70:73], v[156:159], v[208:211], 0
	v_mfma_f32_16x16x32_bf16 v[66:69], v[164:167], v[208:211], 0
	v_mfma_f32_16x16x32_bf16 v[122:125], v[160:163], v[176:179], v[122:125]
	v_mfma_f32_16x16x32_bf16 v[118:121], v[168:171], v[176:179], v[118:121]
	v_mfma_f32_16x16x32_bf16 v[106:109], v[160:163], v[184:187], v[106:109]
	v_mfma_f32_16x16x32_bf16 v[102:105], v[168:171], v[184:187], v[102:105]
	v_mfma_f32_16x16x32_bf16 v[86:89], v[160:163], v[192:195], v[86:89]
	v_mfma_f32_16x16x32_bf16 v[82:85], v[168:171], v[192:195], v[82:85]
	v_mfma_f32_16x16x32_bf16 v[70:73], v[160:163], v[212:215], v[70:73]
	v_mfma_f32_16x16x32_bf16 v[66:69], v[168:171], v[212:215], v[66:69]
	s_setprio 0
	s_barrier
	s_add_i32 s56, s56, s25
	s_mov_b32 m0, s56
	ds_read_b128 v[172:175], v236 offset:16384
	ds_read_b128 v[176:179], v236 offset:17408
	ds_read_b128 v[180:183], v236 offset:18432
	ds_read_b128 v[184:187], v236 offset:19456
	ds_read_b128 v[188:191], v236 offset:20480
	ds_read_b128 v[192:195], v236 offset:21504
	ds_read_b128 v[208:211], v236 offset:22528
	ds_read_b128 v[212:215], v236 offset:23552
	global_load_lds_dwordx4 v0, s[54:55]
	s_add_i32 m0, s56, 0x2000
	s_nop 0
	global_load_lds_dwordx4 v94, s[54:55]
	s_add_u32 s54, s54, s6
	s_addc_u32 s55, s55, 0
	s_add_i32 s56, s57, s25
	s_mov_b32 m0, s56
	s_nop 0
	global_load_lds_dwordx4 v0, s[54:55]
	s_add_i32 m0, s56, 0x2000
	s_nop 0
	global_load_lds_dwordx4 v94, s[54:55]
	s_mov_b32 m0, s28
	s_nop 0
	global_load_lds_dwordx4 v0, s[30:31]
	s_mov_b32 m0, s29
	s_nop 0
	global_load_lds_dwordx4 v94, s[30:31]
	s_waitcnt vmcnt(8)
	s_waitcnt lgkmcnt(0)
	s_barrier
	s_setprio 1
	s_waitcnt lgkmcnt(0)
	v_mfma_f32_16x16x32_bf16 v[62:65], v[140:143], v[172:175], 0
	v_mfma_f32_16x16x32_bf16 v[58:61], v[148:151], v[172:175], 0
	v_mfma_f32_16x16x32_bf16 v[46:49], v[140:143], v[180:183], 0
	v_mfma_f32_16x16x32_bf16 v[42:45], v[148:151], v[180:183], 0
	v_mfma_f32_16x16x32_bf16 v[30:33], v[140:143], v[188:191], 0
	v_mfma_f32_16x16x32_bf16 v[26:29], v[148:151], v[188:191], 0
	v_mfma_f32_16x16x32_bf16 v[14:17], v[140:143], v[208:211], 0
	v_mfma_f32_16x16x32_bf16 v[10:13], v[148:151], v[208:211], 0
	v_mfma_f32_16x16x32_bf16 v[62:65], v[144:147], v[176:179], v[62:65]
	v_mfma_f32_16x16x32_bf16 v[58:61], v[152:155], v[176:179], v[58:61]
	v_mfma_f32_16x16x32_bf16 v[46:49], v[144:147], v[184:187], v[46:49]
	v_mfma_f32_16x16x32_bf16 v[42:45], v[152:155], v[184:187], v[42:45]
	v_mfma_f32_16x16x32_bf16 v[30:33], v[144:147], v[192:195], v[30:33]
	v_mfma_f32_16x16x32_bf16 v[26:29], v[152:155], v[192:195], v[26:29]
	v_mfma_f32_16x16x32_bf16 v[14:17], v[144:147], v[212:215], v[14:17]
	v_mfma_f32_16x16x32_bf16 v[10:13], v[152:155], v[212:215], v[10:13]
	v_mfma_f32_16x16x32_bf16 v[54:57], v[156:159], v[172:175], 0
	v_mfma_f32_16x16x32_bf16 v[50:53], v[164:167], v[172:175], 0
	v_mfma_f32_16x16x32_bf16 v[38:41], v[156:159], v[180:183], 0
	v_mfma_f32_16x16x32_bf16 v[34:37], v[164:167], v[180:183], 0
	v_mfma_f32_16x16x32_bf16 v[22:25], v[156:159], v[188:191], 0
	v_mfma_f32_16x16x32_bf16 v[18:21], v[164:167], v[188:191], 0
	v_mfma_f32_16x16x32_bf16 v[6:9], v[156:159], v[208:211], 0
	v_mfma_f32_16x16x32_bf16 v[2:5], v[164:167], v[208:211], 0
	v_mfma_f32_16x16x32_bf16 v[54:57], v[160:163], v[176:179], v[54:57]
	v_mfma_f32_16x16x32_bf16 v[50:53], v[168:171], v[176:179], v[50:53]
	v_mfma_f32_16x16x32_bf16 v[38:41], v[160:163], v[184:187], v[38:41]
	v_mfma_f32_16x16x32_bf16 v[34:37], v[168:171], v[184:187], v[34:37]
	v_mfma_f32_16x16x32_bf16 v[22:25], v[160:163], v[192:195], v[22:25]
	v_mfma_f32_16x16x32_bf16 v[18:21], v[168:171], v[192:195], v[18:21]
	v_mfma_f32_16x16x32_bf16 v[6:9], v[160:163], v[212:215], v[6:9]
	v_mfma_f32_16x16x32_bf16 v[2:5], v[168:171], v[212:215], v[2:5]
	s_setprio 0
	s_barrier
	s_add_i32 s56, 0, 0x18000
	s_add_i32 s57, 0, 0x1c000
	v_add_u32_e32 v152, s56, v232
	v_add_u32_e32 v168, s57, v232
	ds_read_b128 v[140:143], v152
	ds_read_b128 v[144:147], v152 offset:1024
	ds_read_b128 v[148:151], v152 offset:2048
	ds_read_b128 v[152:155], v152 offset:3072
	ds_read_b128 v[156:159], v168
	ds_read_b128 v[160:163], v168 offset:1024
	ds_read_b128 v[164:167], v168 offset:2048
	ds_read_b128 v[168:171], v168 offset:3072
	s_add_u32 s30, s30, s6
	s_addc_u32 s31, s31, 0
	s_mov_b32 m0, s33
	ds_read_b128 v[172:175], v236 offset:32768
	ds_read_b128 v[176:179], v236 offset:33792
	ds_read_b128 v[180:183], v236 offset:34816
	ds_read_b128 v[184:187], v236 offset:35840
	ds_read_b128 v[188:191], v236 offset:36864
	ds_read_b128 v[192:195], v236 offset:37888
	ds_read_b128 v[208:211], v236 offset:38912
	ds_read_b128 v[212:215], v236 offset:39936
	global_load_lds_dwordx4 v0, s[30:31]
	s_mov_b32 m0, s42
	s_nop 0
	global_load_lds_dwordx4 v94, s[30:31]
	s_waitcnt vmcnt(8)
	s_waitcnt lgkmcnt(0)
	s_barrier
	s_setprio 1
	s_waitcnt lgkmcnt(0)
	v_mfma_f32_16x16x32_bf16 v[130:133], v[140:143], v[172:175], v[130:133]
	v_mfma_f32_16x16x32_bf16 v[126:129], v[148:151], v[172:175], v[126:129]
	v_mfma_f32_16x16x32_bf16 v[114:117], v[140:143], v[180:183], v[114:117]
	v_mfma_f32_16x16x32_bf16 v[110:113], v[148:151], v[180:183], v[110:113]
	v_mfma_f32_16x16x32_bf16 v[98:101], v[140:143], v[188:191], v[98:101]
	v_mfma_f32_16x16x32_bf16 v[90:93], v[148:151], v[188:191], v[90:93]
	v_mfma_f32_16x16x32_bf16 v[78:81], v[140:143], v[208:211], v[78:81]
	v_mfma_f32_16x16x32_bf16 v[74:77], v[148:151], v[208:211], v[74:77]
	v_mfma_f32_16x16x32_bf16 v[130:133], v[144:147], v[176:179], v[130:133]
	v_mfma_f32_16x16x32_bf16 v[126:129], v[152:155], v[176:179], v[126:129]
	v_mfma_f32_16x16x32_bf16 v[114:117], v[144:147], v[184:187], v[114:117]
	v_mfma_f32_16x16x32_bf16 v[110:113], v[152:155], v[184:187], v[110:113]
	v_mfma_f32_16x16x32_bf16 v[98:101], v[144:147], v[192:195], v[98:101]
	v_mfma_f32_16x16x32_bf16 v[90:93], v[152:155], v[192:195], v[90:93]
	v_mfma_f32_16x16x32_bf16 v[78:81], v[144:147], v[212:215], v[78:81]
	v_mfma_f32_16x16x32_bf16 v[74:77], v[152:155], v[212:215], v[74:77]
	v_mfma_f32_16x16x32_bf16 v[122:125], v[156:159], v[172:175], v[122:125]
	v_mfma_f32_16x16x32_bf16 v[118:121], v[164:167], v[172:175], v[118:121]
	v_mfma_f32_16x16x32_bf16 v[106:109], v[156:159], v[180:183], v[106:109]
	v_mfma_f32_16x16x32_bf16 v[102:105], v[164:167], v[180:183], v[102:105]
	v_mfma_f32_16x16x32_bf16 v[86:89], v[156:159], v[188:191], v[86:89]
	v_mfma_f32_16x16x32_bf16 v[82:85], v[164:167], v[188:191], v[82:85]
	v_mfma_f32_16x16x32_bf16 v[70:73], v[156:159], v[208:211], v[70:73]
	v_mfma_f32_16x16x32_bf16 v[66:69], v[164:167], v[208:211], v[66:69]
	v_mfma_f32_16x16x32_bf16 v[122:125], v[160:163], v[176:179], v[122:125]
	v_mfma_f32_16x16x32_bf16 v[118:121], v[168:171], v[176:179], v[118:121]
	v_mfma_f32_16x16x32_bf16 v[106:109], v[160:163], v[184:187], v[106:109]
	v_mfma_f32_16x16x32_bf16 v[102:105], v[168:171], v[184:187], v[102:105]
	v_mfma_f32_16x16x32_bf16 v[86:89], v[160:163], v[192:195], v[86:89]
	v_mfma_f32_16x16x32_bf16 v[82:85], v[168:171], v[192:195], v[82:85]
	v_mfma_f32_16x16x32_bf16 v[70:73], v[160:163], v[212:215], v[70:73]
	v_mfma_f32_16x16x32_bf16 v[66:69], v[168:171], v[212:215], v[66:69]
	s_setprio 0
	s_barrier
	s_add_i32 s71, s56, s25
	s_sub_u32 s54, s54, s6
	s_subb_u32 s55, s55, 0
	s_add_u32 s54, s54, 0x80
	s_addc_u32 s55, s55, 0
	s_mov_b32 m0, s71
	ds_read_b128 v[172:175], v236 offset:49152
	ds_read_b128 v[176:179], v236 offset:50176
	ds_read_b128 v[180:183], v236 offset:51200
	ds_read_b128 v[184:187], v236 offset:52224
	ds_read_b128 v[188:191], v236 offset:53248
	ds_read_b128 v[192:195], v236 offset:54272
	ds_read_b128 v[208:211], v236 offset:55296
	ds_read_b128 v[212:215], v236 offset:56320
	global_load_lds_dwordx4 v0, s[54:55]
	s_add_i32 m0, s71, 0x2000
	s_nop 0
	global_load_lds_dwordx4 v94, s[54:55]
	s_add_i32 s71, s57, s25
	s_add_u32 s54, s54, s6
	s_addc_u32 s55, s55, 0
	s_mov_b32 m0, s71
	s_nop 0
	global_load_lds_dwordx4 v0, s[54:55]
	s_add_i32 m0, s71, 0x2000
	s_nop 0
	global_load_lds_dwordx4 v94, s[54:55]
	s_sub_u32 s30, s30, s6
	s_subb_u32 s31, s31, 0
	s_add_u32 s30, s30, 0x80
	s_addc_u32 s31, s31, 0
	s_mov_b32 m0, s43
	s_nop 0
	global_load_lds_dwordx4 v0, s[30:31]
	s_mov_b32 m0, s44
	s_nop 0
	global_load_lds_dwordx4 v94, s[30:31]
	s_waitcnt vmcnt(8)
	s_waitcnt lgkmcnt(0)
	s_barrier
	s_setprio 1
	s_waitcnt lgkmcnt(0)
	v_mfma_f32_16x16x32_bf16 v[62:65], v[140:143], v[172:175], v[62:65]
	v_mfma_f32_16x16x32_bf16 v[58:61], v[148:151], v[172:175], v[58:61]
	v_mfma_f32_16x16x32_bf16 v[46:49], v[140:143], v[180:183], v[46:49]
	v_mfma_f32_16x16x32_bf16 v[42:45], v[148:151], v[180:183], v[42:45]
	v_mfma_f32_16x16x32_bf16 v[30:33], v[140:143], v[188:191], v[30:33]
	v_mfma_f32_16x16x32_bf16 v[26:29], v[148:151], v[188:191], v[26:29]
	v_mfma_f32_16x16x32_bf16 v[14:17], v[140:143], v[208:211], v[14:17]
	v_mfma_f32_16x16x32_bf16 v[10:13], v[148:151], v[208:211], v[10:13]
	v_mfma_f32_16x16x32_bf16 v[62:65], v[144:147], v[176:179], v[62:65]
	v_mfma_f32_16x16x32_bf16 v[58:61], v[152:155], v[176:179], v[58:61]
	v_mfma_f32_16x16x32_bf16 v[46:49], v[144:147], v[184:187], v[46:49]
	v_mfma_f32_16x16x32_bf16 v[42:45], v[152:155], v[184:187], v[42:45]
	v_mfma_f32_16x16x32_bf16 v[30:33], v[144:147], v[192:195], v[30:33]
	v_mfma_f32_16x16x32_bf16 v[26:29], v[152:155], v[192:195], v[26:29]
	v_mfma_f32_16x16x32_bf16 v[14:17], v[144:147], v[212:215], v[14:17]
	v_mfma_f32_16x16x32_bf16 v[10:13], v[152:155], v[212:215], v[10:13]
	v_mfma_f32_16x16x32_bf16 v[54:57], v[156:159], v[172:175], v[54:57]
	v_mfma_f32_16x16x32_bf16 v[50:53], v[164:167], v[172:175], v[50:53]
	v_mfma_f32_16x16x32_bf16 v[38:41], v[156:159], v[180:183], v[38:41]
	v_mfma_f32_16x16x32_bf16 v[34:37], v[164:167], v[180:183], v[34:37]
	v_mfma_f32_16x16x32_bf16 v[22:25], v[156:159], v[188:191], v[22:25]
	v_mfma_f32_16x16x32_bf16 v[18:21], v[164:167], v[188:191], v[18:21]
	v_mfma_f32_16x16x32_bf16 v[6:9], v[156:159], v[208:211], v[6:9]
	v_mfma_f32_16x16x32_bf16 v[2:5], v[164:167], v[208:211], v[2:5]
	v_mfma_f32_16x16x32_bf16 v[54:57], v[160:163], v[176:179], v[54:57]
	v_mfma_f32_16x16x32_bf16 v[50:53], v[168:171], v[176:179], v[50:53]
	v_mfma_f32_16x16x32_bf16 v[38:41], v[160:163], v[184:187], v[38:41]
	v_mfma_f32_16x16x32_bf16 v[34:37], v[168:171], v[184:187], v[34:37]
	v_mfma_f32_16x16x32_bf16 v[22:25], v[160:163], v[192:195], v[22:25]
	v_mfma_f32_16x16x32_bf16 v[18:21], v[168:171], v[192:195], v[18:21]
	v_mfma_f32_16x16x32_bf16 v[6:9], v[160:163], v[212:215], v[6:9]
	v_mfma_f32_16x16x32_bf16 v[2:5], v[168:171], v[212:215], v[2:5]
	s_setprio 0
	s_barrier
	s_add_u32 s51, s51, 0x100
	s_addc_u32 s52, s52, 0
	s_add_u32 s22, s22, 0x100
	s_addc_u32 s23, s23, 0
	s_mov_b32 s30, s53
.LBB0_528:
	s_add_i32 s53, s30, 2
	s_add_u32 s54, s22, 0x80
	s_addc_u32 s31, s23, 0
	s_add_i32 s56, 0, 0x10000
	s_cmp_eq_u32 s46, s30
	s_cselect_b32 s31, s1, s31
	s_cselect_b32 s30, s0, s54
	s_cselect_b32 s55, s21, s52
	s_cselect_b32 s54, s20, s51
	s_add_i32 s57, 0, 0x14000
	v_add_u32_e32 v152, s56, v232
	v_add_u32_e32 v168, s57, v232
	ds_read_b128 v[140:143], v152
	ds_read_b128 v[144:147], v152 offset:1024
	ds_read_b128 v[148:151], v152 offset:2048
	ds_read_b128 v[152:155], v152 offset:3072
	ds_read_b128 v[156:159], v168
	ds_read_b128 v[160:163], v168 offset:1024
	ds_read_b128 v[164:167], v168 offset:2048
	ds_read_b128 v[168:171], v168 offset:3072
	s_add_i32 m0, s28, 0xc000
	ds_read_b128 v[172:175], v236
	ds_read_b128 v[176:179], v236 offset:1024
	ds_read_b128 v[180:183], v236 offset:2048
	ds_read_b128 v[184:187], v236 offset:3072
	ds_read_b128 v[188:191], v236 offset:4096
	ds_read_b128 v[192:195], v236 offset:5120
	ds_read_b128 v[208:211], v236 offset:6144
	ds_read_b128 v[212:215], v236 offset:7168
	global_load_lds_dwordx4 v138, s[22:23]
	s_add_i32 m0, s28, 0xe000
	s_nop 0
	global_load_lds_dwordx4 v136, s[22:23]
	s_waitcnt vmcnt(8)
	s_waitcnt lgkmcnt(0)
	s_barrier
	s_setprio 1
	s_waitcnt lgkmcnt(0)
	v_mfma_f32_16x16x32_bf16 v[130:133], v[140:143], v[172:175], v[130:133]
	v_mfma_f32_16x16x32_bf16 v[126:129], v[148:151], v[172:175], v[126:129]
	v_mfma_f32_16x16x32_bf16 v[114:117], v[140:143], v[180:183], v[114:117]
	v_mfma_f32_16x16x32_bf16 v[110:113], v[148:151], v[180:183], v[110:113]
	v_mfma_f32_16x16x32_bf16 v[98:101], v[140:143], v[188:191], v[98:101]
	v_mfma_f32_16x16x32_bf16 v[90:93], v[148:151], v[188:191], v[90:93]
	v_mfma_f32_16x16x32_bf16 v[78:81], v[140:143], v[208:211], v[78:81]
	v_mfma_f32_16x16x32_bf16 v[74:77], v[148:151], v[208:211], v[74:77]
	v_mfma_f32_16x16x32_bf16 v[130:133], v[144:147], v[176:179], v[130:133]
	v_mfma_f32_16x16x32_bf16 v[126:129], v[152:155], v[176:179], v[126:129]
	v_mfma_f32_16x16x32_bf16 v[114:117], v[144:147], v[184:187], v[114:117]
	v_mfma_f32_16x16x32_bf16 v[110:113], v[152:155], v[184:187], v[110:113]
	v_mfma_f32_16x16x32_bf16 v[98:101], v[144:147], v[192:195], v[98:101]
	v_mfma_f32_16x16x32_bf16 v[90:93], v[152:155], v[192:195], v[90:93]
	v_mfma_f32_16x16x32_bf16 v[78:81], v[144:147], v[212:215], v[78:81]
	v_mfma_f32_16x16x32_bf16 v[74:77], v[152:155], v[212:215], v[74:77]
	v_mfma_f32_16x16x32_bf16 v[122:125], v[156:159], v[172:175], v[122:125]
	v_mfma_f32_16x16x32_bf16 v[118:121], v[164:167], v[172:175], v[118:121]
	v_mfma_f32_16x16x32_bf16 v[106:109], v[156:159], v[180:183], v[106:109]
	v_mfma_f32_16x16x32_bf16 v[102:105], v[164:167], v[180:183], v[102:105]
	v_mfma_f32_16x16x32_bf16 v[86:89], v[156:159], v[188:191], v[86:89]
	v_mfma_f32_16x16x32_bf16 v[82:85], v[164:167], v[188:191], v[82:85]
	v_mfma_f32_16x16x32_bf16 v[70:73], v[156:159], v[208:211], v[70:73]
	v_mfma_f32_16x16x32_bf16 v[66:69], v[164:167], v[208:211], v[66:69]
	v_mfma_f32_16x16x32_bf16 v[122:125], v[160:163], v[176:179], v[122:125]
	v_mfma_f32_16x16x32_bf16 v[118:121], v[168:171], v[176:179], v[118:121]
	v_mfma_f32_16x16x32_bf16 v[106:109], v[160:163], v[184:187], v[106:109]
	v_mfma_f32_16x16x32_bf16 v[102:105], v[168:171], v[184:187], v[102:105]
	v_mfma_f32_16x16x32_bf16 v[86:89], v[160:163], v[192:195], v[86:89]
	v_mfma_f32_16x16x32_bf16 v[82:85], v[168:171], v[192:195], v[82:85]
	v_mfma_f32_16x16x32_bf16 v[70:73], v[160:163], v[212:215], v[70:73]
	v_mfma_f32_16x16x32_bf16 v[66:69], v[168:171], v[212:215], v[66:69]
	s_setprio 0
	s_barrier
	s_add_i32 s56, s56, s25
	s_mov_b32 m0, s56
	ds_read_b128 v[172:175], v236 offset:16384
	ds_read_b128 v[176:179], v236 offset:17408
	ds_read_b128 v[180:183], v236 offset:18432
	ds_read_b128 v[184:187], v236 offset:19456
	ds_read_b128 v[188:191], v236 offset:20480
	ds_read_b128 v[192:195], v236 offset:21504
	ds_read_b128 v[208:211], v236 offset:22528
	ds_read_b128 v[212:215], v236 offset:23552
	global_load_lds_dwordx4 v0, s[54:55]
	s_add_i32 m0, s56, 0x2000
	s_nop 0
	global_load_lds_dwordx4 v94, s[54:55]
	s_add_u32 s54, s54, s6
	s_addc_u32 s55, s55, 0
	s_add_i32 s56, s57, s25
	s_mov_b32 m0, s56
	s_nop 0
	global_load_lds_dwordx4 v0, s[54:55]
	s_add_i32 m0, s56, 0x2000
	s_nop 0
	global_load_lds_dwordx4 v94, s[54:55]
	s_mov_b32 m0, s28
	s_nop 0
	global_load_lds_dwordx4 v0, s[30:31]
	s_mov_b32 m0, s29
	s_nop 0
	global_load_lds_dwordx4 v94, s[30:31]
	s_waitcnt vmcnt(8)
	s_waitcnt lgkmcnt(0)
	s_barrier
	s_setprio 1
	s_waitcnt lgkmcnt(0)
	v_mfma_f32_16x16x32_bf16 v[62:65], v[140:143], v[172:175], v[62:65]
	v_mfma_f32_16x16x32_bf16 v[58:61], v[148:151], v[172:175], v[58:61]
	v_mfma_f32_16x16x32_bf16 v[46:49], v[140:143], v[180:183], v[46:49]
	v_mfma_f32_16x16x32_bf16 v[42:45], v[148:151], v[180:183], v[42:45]
	v_mfma_f32_16x16x32_bf16 v[30:33], v[140:143], v[188:191], v[30:33]
	v_mfma_f32_16x16x32_bf16 v[26:29], v[148:151], v[188:191], v[26:29]
	v_mfma_f32_16x16x32_bf16 v[14:17], v[140:143], v[208:211], v[14:17]
	v_mfma_f32_16x16x32_bf16 v[10:13], v[148:151], v[208:211], v[10:13]
	v_mfma_f32_16x16x32_bf16 v[62:65], v[144:147], v[176:179], v[62:65]
	v_mfma_f32_16x16x32_bf16 v[58:61], v[152:155], v[176:179], v[58:61]
	v_mfma_f32_16x16x32_bf16 v[46:49], v[144:147], v[184:187], v[46:49]
	v_mfma_f32_16x16x32_bf16 v[42:45], v[152:155], v[184:187], v[42:45]
	v_mfma_f32_16x16x32_bf16 v[30:33], v[144:147], v[192:195], v[30:33]
	v_mfma_f32_16x16x32_bf16 v[26:29], v[152:155], v[192:195], v[26:29]
	v_mfma_f32_16x16x32_bf16 v[14:17], v[144:147], v[212:215], v[14:17]
	v_mfma_f32_16x16x32_bf16 v[10:13], v[152:155], v[212:215], v[10:13]
	v_mfma_f32_16x16x32_bf16 v[54:57], v[156:159], v[172:175], v[54:57]
	v_mfma_f32_16x16x32_bf16 v[50:53], v[164:167], v[172:175], v[50:53]
	v_mfma_f32_16x16x32_bf16 v[38:41], v[156:159], v[180:183], v[38:41]
	v_mfma_f32_16x16x32_bf16 v[34:37], v[164:167], v[180:183], v[34:37]
	v_mfma_f32_16x16x32_bf16 v[22:25], v[156:159], v[188:191], v[22:25]
	v_mfma_f32_16x16x32_bf16 v[18:21], v[164:167], v[188:191], v[18:21]
	v_mfma_f32_16x16x32_bf16 v[6:9], v[156:159], v[208:211], v[6:9]
	v_mfma_f32_16x16x32_bf16 v[2:5], v[164:167], v[208:211], v[2:5]
	v_mfma_f32_16x16x32_bf16 v[54:57], v[160:163], v[176:179], v[54:57]
	v_mfma_f32_16x16x32_bf16 v[50:53], v[168:171], v[176:179], v[50:53]
	v_mfma_f32_16x16x32_bf16 v[38:41], v[160:163], v[184:187], v[38:41]
	v_mfma_f32_16x16x32_bf16 v[34:37], v[168:171], v[184:187], v[34:37]
	v_mfma_f32_16x16x32_bf16 v[22:25], v[160:163], v[192:195], v[22:25]
	v_mfma_f32_16x16x32_bf16 v[18:21], v[168:171], v[192:195], v[18:21]
	v_mfma_f32_16x16x32_bf16 v[6:9], v[160:163], v[212:215], v[6:9]
	v_mfma_f32_16x16x32_bf16 v[2:5], v[168:171], v[212:215], v[2:5]
	s_setprio 0
	s_barrier
	s_add_i32 s56, 0, 0x18000
	s_add_i32 s57, 0, 0x1c000
	v_add_u32_e32 v152, s56, v232
	v_add_u32_e32 v168, s57, v232
	ds_read_b128 v[140:143], v152
	ds_read_b128 v[144:147], v152 offset:1024
	ds_read_b128 v[148:151], v152 offset:2048
	ds_read_b128 v[152:155], v152 offset:3072
	ds_read_b128 v[156:159], v168
	ds_read_b128 v[160:163], v168 offset:1024
	ds_read_b128 v[164:167], v168 offset:2048
	ds_read_b128 v[168:171], v168 offset:3072
	s_add_u32 s30, s30, s6
	s_addc_u32 s31, s31, 0
	s_mov_b32 m0, s33
	ds_read_b128 v[172:175], v236 offset:32768
	ds_read_b128 v[176:179], v236 offset:33792
	ds_read_b128 v[180:183], v236 offset:34816
	ds_read_b128 v[184:187], v236 offset:35840
	ds_read_b128 v[188:191], v236 offset:36864
	ds_read_b128 v[192:195], v236 offset:37888
	ds_read_b128 v[208:211], v236 offset:38912
	ds_read_b128 v[212:215], v236 offset:39936
	global_load_lds_dwordx4 v0, s[30:31]
	s_mov_b32 m0, s42
	s_nop 0
	global_load_lds_dwordx4 v94, s[30:31]
	s_waitcnt vmcnt(8)
	s_waitcnt lgkmcnt(0)
	s_barrier
	s_setprio 1
	s_waitcnt lgkmcnt(0)
	v_mfma_f32_16x16x32_bf16 v[130:133], v[140:143], v[172:175], v[130:133]
	v_mfma_f32_16x16x32_bf16 v[126:129], v[148:151], v[172:175], v[126:129]
	v_mfma_f32_16x16x32_bf16 v[114:117], v[140:143], v[180:183], v[114:117]
	v_mfma_f32_16x16x32_bf16 v[110:113], v[148:151], v[180:183], v[110:113]
	v_mfma_f32_16x16x32_bf16 v[98:101], v[140:143], v[188:191], v[98:101]
	v_mfma_f32_16x16x32_bf16 v[90:93], v[148:151], v[188:191], v[90:93]
	v_mfma_f32_16x16x32_bf16 v[78:81], v[140:143], v[208:211], v[78:81]
	v_mfma_f32_16x16x32_bf16 v[74:77], v[148:151], v[208:211], v[74:77]
	v_mfma_f32_16x16x32_bf16 v[130:133], v[144:147], v[176:179], v[130:133]
	v_mfma_f32_16x16x32_bf16 v[126:129], v[152:155], v[176:179], v[126:129]
	v_mfma_f32_16x16x32_bf16 v[114:117], v[144:147], v[184:187], v[114:117]
	v_mfma_f32_16x16x32_bf16 v[110:113], v[152:155], v[184:187], v[110:113]
	v_mfma_f32_16x16x32_bf16 v[98:101], v[144:147], v[192:195], v[98:101]
	v_mfma_f32_16x16x32_bf16 v[90:93], v[152:155], v[192:195], v[90:93]
	v_mfma_f32_16x16x32_bf16 v[78:81], v[144:147], v[212:215], v[78:81]
	v_mfma_f32_16x16x32_bf16 v[74:77], v[152:155], v[212:215], v[74:77]
	v_mfma_f32_16x16x32_bf16 v[122:125], v[156:159], v[172:175], v[122:125]
	v_mfma_f32_16x16x32_bf16 v[118:121], v[164:167], v[172:175], v[118:121]
	v_mfma_f32_16x16x32_bf16 v[106:109], v[156:159], v[180:183], v[106:109]
	v_mfma_f32_16x16x32_bf16 v[102:105], v[164:167], v[180:183], v[102:105]
	v_mfma_f32_16x16x32_bf16 v[86:89], v[156:159], v[188:191], v[86:89]
	v_mfma_f32_16x16x32_bf16 v[82:85], v[164:167], v[188:191], v[82:85]
	v_mfma_f32_16x16x32_bf16 v[70:73], v[156:159], v[208:211], v[70:73]
	v_mfma_f32_16x16x32_bf16 v[66:69], v[164:167], v[208:211], v[66:69]
	v_mfma_f32_16x16x32_bf16 v[122:125], v[160:163], v[176:179], v[122:125]
	v_mfma_f32_16x16x32_bf16 v[118:121], v[168:171], v[176:179], v[118:121]
	v_mfma_f32_16x16x32_bf16 v[106:109], v[160:163], v[184:187], v[106:109]
	v_mfma_f32_16x16x32_bf16 v[102:105], v[168:171], v[184:187], v[102:105]
	v_mfma_f32_16x16x32_bf16 v[86:89], v[160:163], v[192:195], v[86:89]
	v_mfma_f32_16x16x32_bf16 v[82:85], v[168:171], v[192:195], v[82:85]
	v_mfma_f32_16x16x32_bf16 v[70:73], v[160:163], v[212:215], v[70:73]
	v_mfma_f32_16x16x32_bf16 v[66:69], v[168:171], v[212:215], v[66:69]
	s_setprio 0
	s_barrier
	s_add_i32 s71, s56, s25
	s_sub_u32 s54, s54, s6
	s_subb_u32 s55, s55, 0
	s_add_u32 s54, s54, 0x80
	s_addc_u32 s55, s55, 0
	s_mov_b32 m0, s71
	ds_read_b128 v[172:175], v236 offset:49152
	ds_read_b128 v[176:179], v236 offset:50176
	ds_read_b128 v[180:183], v236 offset:51200
	ds_read_b128 v[184:187], v236 offset:52224
	ds_read_b128 v[188:191], v236 offset:53248
	ds_read_b128 v[192:195], v236 offset:54272
	ds_read_b128 v[208:211], v236 offset:55296
	ds_read_b128 v[212:215], v236 offset:56320
	global_load_lds_dwordx4 v0, s[54:55]
	s_add_i32 m0, s71, 0x2000
	s_nop 0
	global_load_lds_dwordx4 v94, s[54:55]
	s_add_i32 s71, s57, s25
	s_add_u32 s54, s54, s6
	s_addc_u32 s55, s55, 0
	s_mov_b32 m0, s71
	s_nop 0
	global_load_lds_dwordx4 v0, s[54:55]
	s_add_i32 m0, s71, 0x2000
	s_nop 0
	global_load_lds_dwordx4 v94, s[54:55]
	s_sub_u32 s30, s30, s6
	s_subb_u32 s31, s31, 0
	s_add_u32 s30, s30, 0x80
	s_addc_u32 s31, s31, 0
	s_mov_b32 m0, s43
	s_nop 0
	global_load_lds_dwordx4 v0, s[30:31]
	s_mov_b32 m0, s44
	s_nop 0
	global_load_lds_dwordx4 v94, s[30:31]
	s_waitcnt vmcnt(8)
	s_waitcnt lgkmcnt(0)
	s_barrier
	s_setprio 1
	s_waitcnt lgkmcnt(0)
	v_mfma_f32_16x16x32_bf16 v[62:65], v[140:143], v[172:175], v[62:65]
	v_mfma_f32_16x16x32_bf16 v[58:61], v[148:151], v[172:175], v[58:61]
	v_mfma_f32_16x16x32_bf16 v[46:49], v[140:143], v[180:183], v[46:49]
	v_mfma_f32_16x16x32_bf16 v[42:45], v[148:151], v[180:183], v[42:45]
	v_mfma_f32_16x16x32_bf16 v[30:33], v[140:143], v[188:191], v[30:33]
	v_mfma_f32_16x16x32_bf16 v[26:29], v[148:151], v[188:191], v[26:29]
	v_mfma_f32_16x16x32_bf16 v[14:17], v[140:143], v[208:211], v[14:17]
	v_mfma_f32_16x16x32_bf16 v[10:13], v[148:151], v[208:211], v[10:13]
	v_mfma_f32_16x16x32_bf16 v[62:65], v[144:147], v[176:179], v[62:65]
	v_mfma_f32_16x16x32_bf16 v[58:61], v[152:155], v[176:179], v[58:61]
	v_mfma_f32_16x16x32_bf16 v[46:49], v[144:147], v[184:187], v[46:49]
	v_mfma_f32_16x16x32_bf16 v[42:45], v[152:155], v[184:187], v[42:45]
	v_mfma_f32_16x16x32_bf16 v[30:33], v[144:147], v[192:195], v[30:33]
	v_mfma_f32_16x16x32_bf16 v[26:29], v[152:155], v[192:195], v[26:29]
	v_mfma_f32_16x16x32_bf16 v[14:17], v[144:147], v[212:215], v[14:17]
	v_mfma_f32_16x16x32_bf16 v[10:13], v[152:155], v[212:215], v[10:13]
	v_mfma_f32_16x16x32_bf16 v[54:57], v[156:159], v[172:175], v[54:57]
	v_mfma_f32_16x16x32_bf16 v[50:53], v[164:167], v[172:175], v[50:53]
	v_mfma_f32_16x16x32_bf16 v[38:41], v[156:159], v[180:183], v[38:41]
	v_mfma_f32_16x16x32_bf16 v[34:37], v[164:167], v[180:183], v[34:37]
	v_mfma_f32_16x16x32_bf16 v[22:25], v[156:159], v[188:191], v[22:25]
	v_mfma_f32_16x16x32_bf16 v[18:21], v[164:167], v[188:191], v[18:21]
	v_mfma_f32_16x16x32_bf16 v[6:9], v[156:159], v[208:211], v[6:9]
	v_mfma_f32_16x16x32_bf16 v[2:5], v[164:167], v[208:211], v[2:5]
	v_mfma_f32_16x16x32_bf16 v[54:57], v[160:163], v[176:179], v[54:57]
	v_mfma_f32_16x16x32_bf16 v[50:53], v[168:171], v[176:179], v[50:53]
	v_mfma_f32_16x16x32_bf16 v[38:41], v[160:163], v[184:187], v[38:41]
	v_mfma_f32_16x16x32_bf16 v[34:37], v[168:171], v[184:187], v[34:37]
	v_mfma_f32_16x16x32_bf16 v[22:25], v[160:163], v[192:195], v[22:25]
	v_mfma_f32_16x16x32_bf16 v[18:21], v[168:171], v[192:195], v[18:21]
	v_mfma_f32_16x16x32_bf16 v[6:9], v[160:163], v[212:215], v[6:9]
	v_mfma_f32_16x16x32_bf16 v[2:5], v[168:171], v[212:215], v[2:5]
	s_setprio 0
	s_barrier
	s_add_u32 s51, s51, 0x100
	s_addc_u32 s52, s52, 0
	s_add_u32 s22, s22, 0x100
	s_addc_u32 s23, s23, 0
	s_cmp_ge_u32 s53, s45
	s_mov_b32 s30, s53
	s_cbranch_scc0 .LBB0_528
	s_lshl_b32 s19, s19, 8
	v_and_b32_e32 v196, 0xe0, v233
	v_and_b32_e32 v197, 4, v233
	v_lshl_add_u32 v196, v197, 2, v196
	v_and_b32_e32 v197, 8, v233
	v_add_u32_e32 v196, v196, v197
	v_lshl_add_u32 v196, s18, 8, v196
	v_lshlrev_b32_e32 v196, 1, v196
	v_lshl_add_u32 v196, v97, 11, v196
	s_lshl_b32 s22, s19, 11
	s_add_u32 s22, s14, s22
	s_addc_u32 s23, s15, 0
	s_nop 1
	global_load_dwordx4 v[140:143], v196, s[22:23]
	global_load_dwordx4 v[144:147], v196, s[22:23] offset:256
	s_add_u32 s22, s22, 0x8000
	s_addc_u32 s23, s23, 0
	s_nop 1
	global_load_dwordx4 v[148:151], v196, s[22:23]
	global_load_dwordx4 v[152:155], v196, s[22:23] offset:256
	s_add_u32 s22, s22, 0x8000
	s_addc_u32 s23, s23, 0
	s_nop 1
	global_load_dwordx4 v[156:159], v196, s[22:23]
	global_load_dwordx4 v[160:163], v196, s[22:23] offset:256
	s_add_u32 s22, s22, 0x8000
	s_addc_u32 s23, s23, 0
	s_nop 1
	global_load_dwordx4 v[164:167], v196, s[22:23]
	global_load_dwordx4 v[168:171], v196, s[22:23] offset:256
	s_add_u32 s22, s22, 0x28000
	s_addc_u32 s23, s23, 0
	s_nop 1
	global_load_dwordx4 v[172:175], v196, s[22:23]
	global_load_dwordx4 v[176:179], v196, s[22:23] offset:256
	s_add_u32 s22, s22, 0x8000
	s_addc_u32 s23, s23, 0
	s_nop 1
	global_load_dwordx4 v[180:183], v196, s[22:23]
	global_load_dwordx4 v[184:187], v196, s[22:23] offset:256
	s_add_u32 s22, s22, 0x8000
	s_addc_u32 s23, s23, 0
	s_nop 1
	global_load_dwordx4 v[188:191], v196, s[22:23]
	global_load_dwordx4 v[192:195], v196, s[22:23] offset:256
	s_add_u32 s22, s22, 0x8000
	s_addc_u32 s23, s23, 0
	s_nop 1
	global_load_dwordx4 v[208:211], v196, s[22:23]
	global_load_dwordx4 v[212:215], v196, s[22:23] offset:256
	s_and_b64 vcc, exec, s[10:11]
	s_cbranch_vccz .LBB0_531
	s_barrier

.LBB0_564:
	s_ashr_i32 s21, s20, 31
	s_lshl_b64 s[22:23], s[20:21], 19
	s_add_u32 s22, s14, s22
	s_addc_u32 s23, s15, s23
	s_and_b64 s[30:31], s[36:37], exec
	s_cselect_b32 s21, s23, s41
	s_cselect_b32 s47, s22, s40
	s_ashr_i32 s19, s18, 31
	s_lshl_b64 s[30:31], s[18:19], 19
	s_add_u32 s30, s2, s30
	s_addc_u32 s31, s3, s31
	s_and_b64 s[42:43], s[36:37], exec
	s_cselect_b32 s19, s31, s39
	s_cselect_b32 s48, s30, s38
	s_add_u32 s49, s38, 0x100
	s_addc_u32 s50, s39, 0
	s_add_u32 s38, s40, 0x40080
	s_addc_u32 s39, s41, 0
	s_mov_b32 s51, -2
	s_add_u32 s40, s38, 0xfffc0080
	s_addc_u32 s41, s39, -1
	s_add_i32 s52, 0, 0x10000
	s_cmp_eq_u32 s51, 12
	s_cselect_b32 s43, s21, s41
	s_cselect_b32 s42, s47, s40
	v_add_u32_e32 v0, s52, v141
	s_cselect_b32 s41, s19, s50
	s_cselect_b32 s40, s48, s49
	s_add_i32 s54, 0, 0x14000
	ds_read_b128 v[146:149], v0
	ds_read_b128 v[150:153], v0 offset:1024
	ds_read_b128 v[154:157], v0 offset:2048
	ds_read_b128 v[158:161], v0 offset:3072
	v_add_u32_e32 v0, s54, v141
	ds_read_b128 v[162:165], v0
	ds_read_b128 v[166:169], v0 offset:1024
	ds_read_b128 v[170:173], v0 offset:2048
	ds_read_b128 v[174:177], v0 offset:3072
	s_add_i32 m0, s8, 0xc000
	ds_read_b128 v[178:181], v145
	ds_read_b128 v[182:185], v145 offset:1024
	ds_read_b128 v[186:189], v145 offset:2048
	ds_read_b128 v[190:193], v145 offset:3072
	ds_read_b128 v[194:197], v145 offset:4096
	ds_read_b128 v[208:211], v145 offset:5120
	ds_read_b128 v[212:215], v145 offset:6144
	ds_read_b128 v[216:219], v145 offset:7168
	global_load_lds_dwordx4 v138, s[38:39]
	s_add_i32 m0, s8, 0xe000
	s_nop 0
	global_load_lds_dwordx4 v136, s[38:39]
	s_waitcnt vmcnt(8)
	s_waitcnt lgkmcnt(0)
	s_barrier
	s_setprio 1
	s_waitcnt lgkmcnt(0)
	v_mfma_f32_16x16x32_bf16 v[130:133], v[146:149], v[178:181], 0
	v_mfma_f32_16x16x32_bf16 v[126:129], v[154:157], v[178:181], 0
	v_mfma_f32_16x16x32_bf16 v[114:117], v[146:149], v[186:189], 0
	v_mfma_f32_16x16x32_bf16 v[110:113], v[154:157], v[186:189], 0
	v_mfma_f32_16x16x32_bf16 v[98:101], v[146:149], v[194:197], 0
	v_mfma_f32_16x16x32_bf16 v[90:93], v[154:157], v[194:197], 0
	v_mfma_f32_16x16x32_bf16 v[78:81], v[146:149], v[212:215], 0
	v_mfma_f32_16x16x32_bf16 v[74:77], v[154:157], v[212:215], 0
	v_mfma_f32_16x16x32_bf16 v[130:133], v[150:153], v[182:185], v[130:133]
	v_mfma_f32_16x16x32_bf16 v[126:129], v[158:161], v[182:185], v[126:129]
	v_mfma_f32_16x16x32_bf16 v[114:117], v[150:153], v[190:193], v[114:117]
	v_mfma_f32_16x16x32_bf16 v[110:113], v[158:161], v[190:193], v[110:113]
	v_mfma_f32_16x16x32_bf16 v[98:101], v[150:153], v[208:211], v[98:101]
	v_mfma_f32_16x16x32_bf16 v[90:93], v[158:161], v[208:211], v[90:93]
	v_mfma_f32_16x16x32_bf16 v[78:81], v[150:153], v[216:219], v[78:81]
	v_mfma_f32_16x16x32_bf16 v[74:77], v[158:161], v[216:219], v[74:77]
	v_mfma_f32_16x16x32_bf16 v[122:125], v[162:165], v[178:181], 0
	v_mfma_f32_16x16x32_bf16 v[118:121], v[170:173], v[178:181], 0
	v_mfma_f32_16x16x32_bf16 v[106:109], v[162:165], v[186:189], 0
	v_mfma_f32_16x16x32_bf16 v[102:105], v[170:173], v[186:189], 0
	v_mfma_f32_16x16x32_bf16 v[86:89], v[162:165], v[194:197], 0
	v_mfma_f32_16x16x32_bf16 v[82:85], v[170:173], v[194:197], 0
	v_mfma_f32_16x16x32_bf16 v[70:73], v[162:165], v[212:215], 0
	v_mfma_f32_16x16x32_bf16 v[66:69], v[170:173], v[212:215], 0
	v_mfma_f32_16x16x32_bf16 v[122:125], v[166:169], v[182:185], v[122:125]
	v_mfma_f32_16x16x32_bf16 v[118:121], v[174:177], v[182:185], v[118:121]
	v_mfma_f32_16x16x32_bf16 v[106:109], v[166:169], v[190:193], v[106:109]
	v_mfma_f32_16x16x32_bf16 v[102:105], v[174:177], v[190:193], v[102:105]
	v_mfma_f32_16x16x32_bf16 v[86:89], v[166:169], v[208:211], v[86:89]
	v_mfma_f32_16x16x32_bf16 v[82:85], v[174:177], v[208:211], v[82:85]
	v_mfma_f32_16x16x32_bf16 v[70:73], v[166:169], v[216:219], v[70:73]
	v_mfma_f32_16x16x32_bf16 v[66:69], v[174:177], v[216:219], v[66:69]
	s_setprio 0
	s_barrier
	s_add_i32 s52, s52, s6
	s_mov_b32 m0, s52
	ds_read_b128 v[178:181], v145 offset:16384
	ds_read_b128 v[182:185], v145 offset:17408
	ds_read_b128 v[186:189], v145 offset:18432
	ds_read_b128 v[190:193], v145 offset:19456
	ds_read_b128 v[194:197], v145 offset:20480
	ds_read_b128 v[208:211], v145 offset:21504
	ds_read_b128 v[212:215], v145 offset:22528
	ds_read_b128 v[216:219], v145 offset:23552
	global_load_lds_dwordx4 v134, s[40:41]
	s_add_i32 m0, s52, 0x2000
	s_add_u32 s52, s40, 0x40000
	s_addc_u32 s53, s41, 0
	s_add_i32 s54, s54, s6
	global_load_lds_dwordx4 v94, s[40:41]
	s_mov_b32 m0, s54
	s_nop 0
	global_load_lds_dwordx4 v134, s[52:53]
	s_add_i32 m0, s54, 0x2000
	s_nop 0
	global_load_lds_dwordx4 v94, s[52:53]
	s_mov_b32 m0, s8
	s_nop 0
	global_load_lds_dwordx4 v134, s[42:43]
	s_mov_b32 m0, s9
	s_nop 0
	global_load_lds_dwordx4 v94, s[42:43]
	s_waitcnt vmcnt(8)
	s_waitcnt lgkmcnt(0)
	s_barrier
	s_setprio 1
	s_waitcnt lgkmcnt(0)
	v_mfma_f32_16x16x32_bf16 v[62:65], v[146:149], v[178:181], 0
	v_mfma_f32_16x16x32_bf16 v[58:61], v[154:157], v[178:181], 0
	v_mfma_f32_16x16x32_bf16 v[46:49], v[146:149], v[186:189], 0
	v_mfma_f32_16x16x32_bf16 v[42:45], v[154:157], v[186:189], 0
	v_mfma_f32_16x16x32_bf16 v[30:33], v[146:149], v[194:197], 0
	v_mfma_f32_16x16x32_bf16 v[26:29], v[154:157], v[194:197], 0
	v_mfma_f32_16x16x32_bf16 v[14:17], v[146:149], v[212:215], 0
	v_mfma_f32_16x16x32_bf16 v[10:13], v[154:157], v[212:215], 0
	v_mfma_f32_16x16x32_bf16 v[62:65], v[150:153], v[182:185], v[62:65]
	v_mfma_f32_16x16x32_bf16 v[58:61], v[158:161], v[182:185], v[58:61]
	v_mfma_f32_16x16x32_bf16 v[46:49], v[150:153], v[190:193], v[46:49]
	v_mfma_f32_16x16x32_bf16 v[42:45], v[158:161], v[190:193], v[42:45]
	v_mfma_f32_16x16x32_bf16 v[30:33], v[150:153], v[208:211], v[30:33]
	v_mfma_f32_16x16x32_bf16 v[26:29], v[158:161], v[208:211], v[26:29]
	v_mfma_f32_16x16x32_bf16 v[14:17], v[150:153], v[216:219], v[14:17]
	v_mfma_f32_16x16x32_bf16 v[10:13], v[158:161], v[216:219], v[10:13]
	v_mfma_f32_16x16x32_bf16 v[54:57], v[162:165], v[178:181], 0
	v_mfma_f32_16x16x32_bf16 v[50:53], v[170:173], v[178:181], 0
	v_mfma_f32_16x16x32_bf16 v[38:41], v[162:165], v[186:189], 0
	v_mfma_f32_16x16x32_bf16 v[34:37], v[170:173], v[186:189], 0
	v_mfma_f32_16x16x32_bf16 v[22:25], v[162:165], v[194:197], 0
	v_mfma_f32_16x16x32_bf16 v[18:21], v[170:173], v[194:197], 0
	v_mfma_f32_16x16x32_bf16 v[6:9], v[162:165], v[212:215], 0
	v_mfma_f32_16x16x32_bf16 v[2:5], v[170:173], v[212:215], 0
	v_mfma_f32_16x16x32_bf16 v[54:57], v[166:169], v[182:185], v[54:57]
	v_mfma_f32_16x16x32_bf16 v[50:53], v[174:177], v[182:185], v[50:53]
	v_mfma_f32_16x16x32_bf16 v[38:41], v[166:169], v[190:193], v[38:41]
	v_mfma_f32_16x16x32_bf16 v[34:37], v[174:177], v[190:193], v[34:37]
	v_mfma_f32_16x16x32_bf16 v[22:25], v[166:169], v[208:211], v[22:25]
	v_mfma_f32_16x16x32_bf16 v[18:21], v[174:177], v[208:211], v[18:21]
	v_mfma_f32_16x16x32_bf16 v[6:9], v[166:169], v[216:219], v[6:9]
	v_mfma_f32_16x16x32_bf16 v[2:5], v[174:177], v[216:219], v[2:5]
	s_setprio 0
	s_barrier
	s_add_i32 s52, 0, 0x18000
	v_add_u32_e32 v0, s52, v141
	s_add_i32 s53, 0, 0x1c000
	ds_read_b128 v[146:149], v0
	ds_read_b128 v[150:153], v0 offset:1024
	ds_read_b128 v[154:157], v0 offset:2048
	ds_read_b128 v[158:161], v0 offset:3072
	v_add_u32_e32 v0, s53, v141
	ds_read_b128 v[162:165], v0
	ds_read_b128 v[166:169], v0 offset:1024
	ds_read_b128 v[170:173], v0 offset:2048
	ds_read_b128 v[174:177], v0 offset:3072
	s_add_u32 s42, s42, 0x40000
	s_addc_u32 s43, s43, 0
	s_mov_b32 m0, s12
	ds_read_b128 v[178:181], v145 offset:32768
	ds_read_b128 v[182:185], v145 offset:33792
	ds_read_b128 v[186:189], v145 offset:34816
	ds_read_b128 v[190:193], v145 offset:35840
	ds_read_b128 v[194:197], v145 offset:36864
	ds_read_b128 v[208:211], v145 offset:37888
	ds_read_b128 v[212:215], v145 offset:38912
	ds_read_b128 v[216:219], v145 offset:39936
	global_load_lds_dwordx4 v134, s[42:43]
	s_mov_b32 m0, s13
	s_nop 0
	global_load_lds_dwordx4 v94, s[42:43]
	s_waitcnt vmcnt(8)
	s_waitcnt lgkmcnt(0)
	s_barrier
	s_setprio 1
	s_waitcnt lgkmcnt(0)
	v_mfma_f32_16x16x32_bf16 v[130:133], v[146:149], v[178:181], v[130:133]
	v_mfma_f32_16x16x32_bf16 v[126:129], v[154:157], v[178:181], v[126:129]
	v_mfma_f32_16x16x32_bf16 v[114:117], v[146:149], v[186:189], v[114:117]
	v_mfma_f32_16x16x32_bf16 v[110:113], v[154:157], v[186:189], v[110:113]
	v_mfma_f32_16x16x32_bf16 v[98:101], v[146:149], v[194:197], v[98:101]
	v_mfma_f32_16x16x32_bf16 v[90:93], v[154:157], v[194:197], v[90:93]
	v_mfma_f32_16x16x32_bf16 v[78:81], v[146:149], v[212:215], v[78:81]
	v_mfma_f32_16x16x32_bf16 v[74:77], v[154:157], v[212:215], v[74:77]
	v_mfma_f32_16x16x32_bf16 v[130:133], v[150:153], v[182:185], v[130:133]
	v_mfma_f32_16x16x32_bf16 v[126:129], v[158:161], v[182:185], v[126:129]
	v_mfma_f32_16x16x32_bf16 v[114:117], v[150:153], v[190:193], v[114:117]
	v_mfma_f32_16x16x32_bf16 v[110:113], v[158:161], v[190:193], v[110:113]
	v_mfma_f32_16x16x32_bf16 v[98:101], v[150:153], v[208:211], v[98:101]
	v_mfma_f32_16x16x32_bf16 v[90:93], v[158:161], v[208:211], v[90:93]
	v_mfma_f32_16x16x32_bf16 v[78:81], v[150:153], v[216:219], v[78:81]
	v_mfma_f32_16x16x32_bf16 v[74:77], v[158:161], v[216:219], v[74:77]
	v_mfma_f32_16x16x32_bf16 v[122:125], v[162:165], v[178:181], v[122:125]
	v_mfma_f32_16x16x32_bf16 v[118:121], v[170:173], v[178:181], v[118:121]
	v_mfma_f32_16x16x32_bf16 v[106:109], v[162:165], v[186:189], v[106:109]
	v_mfma_f32_16x16x32_bf16 v[102:105], v[170:173], v[186:189], v[102:105]
	v_mfma_f32_16x16x32_bf16 v[86:89], v[162:165], v[194:197], v[86:89]
	v_mfma_f32_16x16x32_bf16 v[82:85], v[170:173], v[194:197], v[82:85]
	v_mfma_f32_16x16x32_bf16 v[70:73], v[162:165], v[212:215], v[70:73]
	v_mfma_f32_16x16x32_bf16 v[66:69], v[170:173], v[212:215], v[66:69]
	v_mfma_f32_16x16x32_bf16 v[122:125], v[166:169], v[182:185], v[122:125]
	v_mfma_f32_16x16x32_bf16 v[118:121], v[174:177], v[182:185], v[118:121]
	v_mfma_f32_16x16x32_bf16 v[106:109], v[166:169], v[190:193], v[106:109]
	v_mfma_f32_16x16x32_bf16 v[102:105], v[174:177], v[190:193], v[102:105]
	v_mfma_f32_16x16x32_bf16 v[86:89], v[166:169], v[208:211], v[86:89]
	v_mfma_f32_16x16x32_bf16 v[82:85], v[174:177], v[208:211], v[82:85]
	v_mfma_f32_16x16x32_bf16 v[70:73], v[166:169], v[216:219], v[70:73]
	v_mfma_f32_16x16x32_bf16 v[66:69], v[174:177], v[216:219], v[66:69]
	s_setprio 0
	s_barrier
	s_add_i32 s54, s52, s6
	s_add_i32 m0, s54, 0xffffff80
	ds_read_b128 v[178:181], v145 offset:49152
	ds_read_b128 v[182:185], v145 offset:50176
	ds_read_b128 v[186:189], v145 offset:51200
	ds_read_b128 v[190:193], v145 offset:52224
	ds_read_b128 v[194:197], v145 offset:53248
	ds_read_b128 v[208:211], v145 offset:54272
	ds_read_b128 v[212:215], v145 offset:55296
	ds_read_b128 v[216:219], v145 offset:56320
	global_load_lds_dwordx4 v134, s[40:41] offset:128
	s_add_i32 m0, s54, 0x1f80
	s_nop 0
	global_load_lds_dwordx4 v94, s[40:41] offset:128
	s_add_i32 s54, s53, s6
	s_add_u32 s40, s40, 0x40080
	s_addc_u32 s41, s41, 0
	s_mov_b32 m0, s54
	s_nop 0
	global_load_lds_dwordx4 v134, s[40:41]
	s_add_i32 m0, s54, 0x2000
	s_nop 0
	global_load_lds_dwordx4 v94, s[40:41]
	s_add_u32 s42, s42, 0xfffc0080
	s_addc_u32 s43, s43, -1
	s_mov_b32 m0, s28
	s_nop 0
	global_load_lds_dwordx4 v134, s[42:43]
	s_mov_b32 m0, s29
	s_nop 0
	global_load_lds_dwordx4 v94, s[42:43]
	s_waitcnt vmcnt(8)
	s_waitcnt lgkmcnt(0)
	s_barrier
	s_setprio 1
	s_waitcnt lgkmcnt(0)
	v_mfma_f32_16x16x32_bf16 v[62:65], v[146:149], v[178:181], v[62:65]
	v_mfma_f32_16x16x32_bf16 v[58:61], v[154:157], v[178:181], v[58:61]
	v_mfma_f32_16x16x32_bf16 v[46:49], v[146:149], v[186:189], v[46:49]
	v_mfma_f32_16x16x32_bf16 v[42:45], v[154:157], v[186:189], v[42:45]
	v_mfma_f32_16x16x32_bf16 v[30:33], v[146:149], v[194:197], v[30:33]
	v_mfma_f32_16x16x32_bf16 v[26:29], v[154:157], v[194:197], v[26:29]
	v_mfma_f32_16x16x32_bf16 v[14:17], v[146:149], v[212:215], v[14:17]
	v_mfma_f32_16x16x32_bf16 v[10:13], v[154:157], v[212:215], v[10:13]
	v_mfma_f32_16x16x32_bf16 v[62:65], v[150:153], v[182:185], v[62:65]
	v_mfma_f32_16x16x32_bf16 v[58:61], v[158:161], v[182:185], v[58:61]
	v_mfma_f32_16x16x32_bf16 v[46:49], v[150:153], v[190:193], v[46:49]
	v_mfma_f32_16x16x32_bf16 v[42:45], v[158:161], v[190:193], v[42:45]
	v_mfma_f32_16x16x32_bf16 v[30:33], v[150:153], v[208:211], v[30:33]
	v_mfma_f32_16x16x32_bf16 v[26:29], v[158:161], v[208:211], v[26:29]
	v_mfma_f32_16x16x32_bf16 v[14:17], v[150:153], v[216:219], v[14:17]
	v_mfma_f32_16x16x32_bf16 v[10:13], v[158:161], v[216:219], v[10:13]
	v_mfma_f32_16x16x32_bf16 v[54:57], v[162:165], v[178:181], v[54:57]
	v_mfma_f32_16x16x32_bf16 v[50:53], v[170:173], v[178:181], v[50:53]
	v_mfma_f32_16x16x32_bf16 v[38:41], v[162:165], v[186:189], v[38:41]
	v_mfma_f32_16x16x32_bf16 v[34:37], v[170:173], v[186:189], v[34:37]
	v_mfma_f32_16x16x32_bf16 v[22:25], v[162:165], v[194:197], v[22:25]
	v_mfma_f32_16x16x32_bf16 v[18:21], v[170:173], v[194:197], v[18:21]
	v_mfma_f32_16x16x32_bf16 v[6:9], v[162:165], v[212:215], v[6:9]
	v_mfma_f32_16x16x32_bf16 v[2:5], v[170:173], v[212:215], v[2:5]
	v_mfma_f32_16x16x32_bf16 v[54:57], v[166:169], v[182:185], v[54:57]
	v_mfma_f32_16x16x32_bf16 v[50:53], v[174:177], v[182:185], v[50:53]
	v_mfma_f32_16x16x32_bf16 v[38:41], v[166:169], v[190:193], v[38:41]
	v_mfma_f32_16x16x32_bf16 v[34:37], v[174:177], v[190:193], v[34:37]
	v_mfma_f32_16x16x32_bf16 v[22:25], v[166:169], v[208:211], v[22:25]
	v_mfma_f32_16x16x32_bf16 v[18:21], v[174:177], v[208:211], v[18:21]
	v_mfma_f32_16x16x32_bf16 v[6:9], v[166:169], v[216:219], v[6:9]
	v_mfma_f32_16x16x32_bf16 v[2:5], v[174:177], v[216:219], v[2:5]
	s_setprio 0
	s_barrier
	s_add_i32 s51, s51, 2
	s_add_u32 s49, s49, 0x100
	s_addc_u32 s50, s50, 0
	s_add_u32 s38, s38, 0x100
	s_addc_u32 s39, s39, 0
.LBB0_565:
	s_add_u32 s40, s38, 0xfffc0080
	s_addc_u32 s41, s39, -1
	s_add_i32 s52, 0, 0x10000
	s_cmp_eq_u32 s51, 12
	s_cselect_b32 s43, s21, s41
	s_cselect_b32 s42, s47, s40
	v_add_u32_e32 v0, s52, v141
	s_cselect_b32 s41, s19, s50
	s_cselect_b32 s40, s48, s49
	s_add_i32 s54, 0, 0x14000
	ds_read_b128 v[146:149], v0
	ds_read_b128 v[150:153], v0 offset:1024
	ds_read_b128 v[154:157], v0 offset:2048
	ds_read_b128 v[158:161], v0 offset:3072
	v_add_u32_e32 v0, s54, v141
	ds_read_b128 v[162:165], v0
	ds_read_b128 v[166:169], v0 offset:1024
	ds_read_b128 v[170:173], v0 offset:2048
	ds_read_b128 v[174:177], v0 offset:3072
	s_add_i32 m0, s8, 0xc000
	ds_read_b128 v[178:181], v145
	ds_read_b128 v[182:185], v145 offset:1024
	ds_read_b128 v[186:189], v145 offset:2048
	ds_read_b128 v[190:193], v145 offset:3072
	ds_read_b128 v[194:197], v145 offset:4096
	ds_read_b128 v[208:211], v145 offset:5120
	ds_read_b128 v[212:215], v145 offset:6144
	ds_read_b128 v[216:219], v145 offset:7168
	global_load_lds_dwordx4 v138, s[38:39]
	s_add_i32 m0, s8, 0xe000
	s_nop 0
	global_load_lds_dwordx4 v136, s[38:39]
	s_waitcnt vmcnt(8)
	s_waitcnt lgkmcnt(0)
	s_barrier
	s_setprio 1
	s_waitcnt lgkmcnt(0)
	v_mfma_f32_16x16x32_bf16 v[130:133], v[146:149], v[178:181], v[130:133]
	v_mfma_f32_16x16x32_bf16 v[126:129], v[154:157], v[178:181], v[126:129]
	v_mfma_f32_16x16x32_bf16 v[114:117], v[146:149], v[186:189], v[114:117]
	v_mfma_f32_16x16x32_bf16 v[110:113], v[154:157], v[186:189], v[110:113]
	v_mfma_f32_16x16x32_bf16 v[98:101], v[146:149], v[194:197], v[98:101]
	v_mfma_f32_16x16x32_bf16 v[90:93], v[154:157], v[194:197], v[90:93]
	v_mfma_f32_16x16x32_bf16 v[78:81], v[146:149], v[212:215], v[78:81]
	v_mfma_f32_16x16x32_bf16 v[74:77], v[154:157], v[212:215], v[74:77]
	v_mfma_f32_16x16x32_bf16 v[130:133], v[150:153], v[182:185], v[130:133]
	v_mfma_f32_16x16x32_bf16 v[126:129], v[158:161], v[182:185], v[126:129]
	v_mfma_f32_16x16x32_bf16 v[114:117], v[150:153], v[190:193], v[114:117]
	v_mfma_f32_16x16x32_bf16 v[110:113], v[158:161], v[190:193], v[110:113]
	v_mfma_f32_16x16x32_bf16 v[98:101], v[150:153], v[208:211], v[98:101]
	v_mfma_f32_16x16x32_bf16 v[90:93], v[158:161], v[208:211], v[90:93]
	v_mfma_f32_16x16x32_bf16 v[78:81], v[150:153], v[216:219], v[78:81]
	v_mfma_f32_16x16x32_bf16 v[74:77], v[158:161], v[216:219], v[74:77]
	v_mfma_f32_16x16x32_bf16 v[122:125], v[162:165], v[178:181], v[122:125]
	v_mfma_f32_16x16x32_bf16 v[118:121], v[170:173], v[178:181], v[118:121]
	v_mfma_f32_16x16x32_bf16 v[106:109], v[162:165], v[186:189], v[106:109]
	v_mfma_f32_16x16x32_bf16 v[102:105], v[170:173], v[186:189], v[102:105]
	v_mfma_f32_16x16x32_bf16 v[86:89], v[162:165], v[194:197], v[86:89]
	v_mfma_f32_16x16x32_bf16 v[82:85], v[170:173], v[194:197], v[82:85]
	v_mfma_f32_16x16x32_bf16 v[70:73], v[162:165], v[212:215], v[70:73]
	v_mfma_f32_16x16x32_bf16 v[66:69], v[170:173], v[212:215], v[66:69]
	v_mfma_f32_16x16x32_bf16 v[122:125], v[166:169], v[182:185], v[122:125]
	v_mfma_f32_16x16x32_bf16 v[118:121], v[174:177], v[182:185], v[118:121]
	v_mfma_f32_16x16x32_bf16 v[106:109], v[166:169], v[190:193], v[106:109]
	v_mfma_f32_16x16x32_bf16 v[102:105], v[174:177], v[190:193], v[102:105]
	v_mfma_f32_16x16x32_bf16 v[86:89], v[166:169], v[208:211], v[86:89]
	v_mfma_f32_16x16x32_bf16 v[82:85], v[174:177], v[208:211], v[82:85]
	v_mfma_f32_16x16x32_bf16 v[70:73], v[166:169], v[216:219], v[70:73]
	v_mfma_f32_16x16x32_bf16 v[66:69], v[174:177], v[216:219], v[66:69]
	s_setprio 0
	s_barrier
	s_add_i32 s52, s52, s6
	s_mov_b32 m0, s52
	ds_read_b128 v[178:181], v145 offset:16384
	ds_read_b128 v[182:185], v145 offset:17408
	ds_read_b128 v[186:189], v145 offset:18432
	ds_read_b128 v[190:193], v145 offset:19456
	ds_read_b128 v[194:197], v145 offset:20480
	ds_read_b128 v[208:211], v145 offset:21504
	ds_read_b128 v[212:215], v145 offset:22528
	ds_read_b128 v[216:219], v145 offset:23552
	global_load_lds_dwordx4 v134, s[40:41]
	s_add_i32 m0, s52, 0x2000
	s_add_u32 s52, s40, 0x40000
	s_addc_u32 s53, s41, 0
	s_add_i32 s54, s54, s6
	global_load_lds_dwordx4 v94, s[40:41]
	s_mov_b32 m0, s54
	s_nop 0
	global_load_lds_dwordx4 v134, s[52:53]
	s_add_i32 m0, s54, 0x2000
	s_nop 0
	global_load_lds_dwordx4 v94, s[52:53]
	s_mov_b32 m0, s8
	s_nop 0
	global_load_lds_dwordx4 v134, s[42:43]
	s_mov_b32 m0, s9
	s_nop 0
	global_load_lds_dwordx4 v94, s[42:43]
	s_waitcnt vmcnt(8)
	s_waitcnt lgkmcnt(0)
	s_barrier
	s_setprio 1
	s_waitcnt lgkmcnt(0)
	v_mfma_f32_16x16x32_bf16 v[62:65], v[146:149], v[178:181], v[62:65]
	v_mfma_f32_16x16x32_bf16 v[58:61], v[154:157], v[178:181], v[58:61]
	v_mfma_f32_16x16x32_bf16 v[46:49], v[146:149], v[186:189], v[46:49]
	v_mfma_f32_16x16x32_bf16 v[42:45], v[154:157], v[186:189], v[42:45]
	v_mfma_f32_16x16x32_bf16 v[30:33], v[146:149], v[194:197], v[30:33]
	v_mfma_f32_16x16x32_bf16 v[26:29], v[154:157], v[194:197], v[26:29]
	v_mfma_f32_16x16x32_bf16 v[14:17], v[146:149], v[212:215], v[14:17]
	v_mfma_f32_16x16x32_bf16 v[10:13], v[154:157], v[212:215], v[10:13]
	v_mfma_f32_16x16x32_bf16 v[62:65], v[150:153], v[182:185], v[62:65]
	v_mfma_f32_16x16x32_bf16 v[58:61], v[158:161], v[182:185], v[58:61]
	v_mfma_f32_16x16x32_bf16 v[46:49], v[150:153], v[190:193], v[46:49]
	v_mfma_f32_16x16x32_bf16 v[42:45], v[158:161], v[190:193], v[42:45]
	v_mfma_f32_16x16x32_bf16 v[30:33], v[150:153], v[208:211], v[30:33]
	v_mfma_f32_16x16x32_bf16 v[26:29], v[158:161], v[208:211], v[26:29]
	v_mfma_f32_16x16x32_bf16 v[14:17], v[150:153], v[216:219], v[14:17]
	v_mfma_f32_16x16x32_bf16 v[10:13], v[158:161], v[216:219], v[10:13]
	v_mfma_f32_16x16x32_bf16 v[54:57], v[162:165], v[178:181], v[54:57]
	v_mfma_f32_16x16x32_bf16 v[50:53], v[170:173], v[178:181], v[50:53]
	v_mfma_f32_16x16x32_bf16 v[38:41], v[162:165], v[186:189], v[38:41]
	v_mfma_f32_16x16x32_bf16 v[34:37], v[170:173], v[186:189], v[34:37]
	v_mfma_f32_16x16x32_bf16 v[22:25], v[162:165], v[194:197], v[22:25]
	v_mfma_f32_16x16x32_bf16 v[18:21], v[170:173], v[194:197], v[18:21]
	v_mfma_f32_16x16x32_bf16 v[6:9], v[162:165], v[212:215], v[6:9]
	v_mfma_f32_16x16x32_bf16 v[2:5], v[170:173], v[212:215], v[2:5]
	v_mfma_f32_16x16x32_bf16 v[54:57], v[166:169], v[182:185], v[54:57]
	v_mfma_f32_16x16x32_bf16 v[50:53], v[174:177], v[182:185], v[50:53]
	v_mfma_f32_16x16x32_bf16 v[38:41], v[166:169], v[190:193], v[38:41]
	v_mfma_f32_16x16x32_bf16 v[34:37], v[174:177], v[190:193], v[34:37]
	v_mfma_f32_16x16x32_bf16 v[22:25], v[166:169], v[208:211], v[22:25]
	v_mfma_f32_16x16x32_bf16 v[18:21], v[174:177], v[208:211], v[18:21]
	v_mfma_f32_16x16x32_bf16 v[6:9], v[166:169], v[216:219], v[6:9]
	v_mfma_f32_16x16x32_bf16 v[2:5], v[174:177], v[216:219], v[2:5]
	s_setprio 0
	s_barrier
	s_add_i32 s52, 0, 0x18000
	v_add_u32_e32 v0, s52, v141
	s_add_i32 s53, 0, 0x1c000
	ds_read_b128 v[146:149], v0
	ds_read_b128 v[150:153], v0 offset:1024
	ds_read_b128 v[154:157], v0 offset:2048
	ds_read_b128 v[158:161], v0 offset:3072
	v_add_u32_e32 v0, s53, v141
	ds_read_b128 v[162:165], v0
	ds_read_b128 v[166:169], v0 offset:1024
	ds_read_b128 v[170:173], v0 offset:2048
	ds_read_b128 v[174:177], v0 offset:3072
	s_add_u32 s42, s42, 0x40000
	s_addc_u32 s43, s43, 0
	s_mov_b32 m0, s12
	ds_read_b128 v[178:181], v145 offset:32768
	ds_read_b128 v[182:185], v145 offset:33792
	ds_read_b128 v[186:189], v145 offset:34816
	ds_read_b128 v[190:193], v145 offset:35840
	ds_read_b128 v[194:197], v145 offset:36864
	ds_read_b128 v[208:211], v145 offset:37888
	ds_read_b128 v[212:215], v145 offset:38912
	ds_read_b128 v[216:219], v145 offset:39936
	global_load_lds_dwordx4 v134, s[42:43]
	s_mov_b32 m0, s13
	s_nop 0
	global_load_lds_dwordx4 v94, s[42:43]
	s_waitcnt vmcnt(8)
	s_waitcnt lgkmcnt(0)
	s_barrier
	s_setprio 1
	s_waitcnt lgkmcnt(0)
	v_mfma_f32_16x16x32_bf16 v[130:133], v[146:149], v[178:181], v[130:133]
	v_mfma_f32_16x16x32_bf16 v[126:129], v[154:157], v[178:181], v[126:129]
	v_mfma_f32_16x16x32_bf16 v[114:117], v[146:149], v[186:189], v[114:117]
	v_mfma_f32_16x16x32_bf16 v[110:113], v[154:157], v[186:189], v[110:113]
	v_mfma_f32_16x16x32_bf16 v[98:101], v[146:149], v[194:197], v[98:101]
	v_mfma_f32_16x16x32_bf16 v[90:93], v[154:157], v[194:197], v[90:93]
	v_mfma_f32_16x16x32_bf16 v[78:81], v[146:149], v[212:215], v[78:81]
	v_mfma_f32_16x16x32_bf16 v[74:77], v[154:157], v[212:215], v[74:77]
	v_mfma_f32_16x16x32_bf16 v[130:133], v[150:153], v[182:185], v[130:133]
	v_mfma_f32_16x16x32_bf16 v[126:129], v[158:161], v[182:185], v[126:129]
	v_mfma_f32_16x16x32_bf16 v[114:117], v[150:153], v[190:193], v[114:117]
	v_mfma_f32_16x16x32_bf16 v[110:113], v[158:161], v[190:193], v[110:113]
	v_mfma_f32_16x16x32_bf16 v[98:101], v[150:153], v[208:211], v[98:101]
	v_mfma_f32_16x16x32_bf16 v[90:93], v[158:161], v[208:211], v[90:93]
	v_mfma_f32_16x16x32_bf16 v[78:81], v[150:153], v[216:219], v[78:81]
	v_mfma_f32_16x16x32_bf16 v[74:77], v[158:161], v[216:219], v[74:77]
	v_mfma_f32_16x16x32_bf16 v[122:125], v[162:165], v[178:181], v[122:125]
	v_mfma_f32_16x16x32_bf16 v[118:121], v[170:173], v[178:181], v[118:121]
	v_mfma_f32_16x16x32_bf16 v[106:109], v[162:165], v[186:189], v[106:109]
	v_mfma_f32_16x16x32_bf16 v[102:105], v[170:173], v[186:189], v[102:105]
	v_mfma_f32_16x16x32_bf16 v[86:89], v[162:165], v[194:197], v[86:89]
	v_mfma_f32_16x16x32_bf16 v[82:85], v[170:173], v[194:197], v[82:85]
	v_mfma_f32_16x16x32_bf16 v[70:73], v[162:165], v[212:215], v[70:73]
	v_mfma_f32_16x16x32_bf16 v[66:69], v[170:173], v[212:215], v[66:69]
	v_mfma_f32_16x16x32_bf16 v[122:125], v[166:169], v[182:185], v[122:125]
	v_mfma_f32_16x16x32_bf16 v[118:121], v[174:177], v[182:185], v[118:121]
	v_mfma_f32_16x16x32_bf16 v[106:109], v[166:169], v[190:193], v[106:109]
	v_mfma_f32_16x16x32_bf16 v[102:105], v[174:177], v[190:193], v[102:105]
	v_mfma_f32_16x16x32_bf16 v[86:89], v[166:169], v[208:211], v[86:89]
	v_mfma_f32_16x16x32_bf16 v[82:85], v[174:177], v[208:211], v[82:85]
	v_mfma_f32_16x16x32_bf16 v[70:73], v[166:169], v[216:219], v[70:73]
	v_mfma_f32_16x16x32_bf16 v[66:69], v[174:177], v[216:219], v[66:69]
	s_setprio 0
	s_barrier
	s_add_i32 s54, s52, s6
	s_add_i32 m0, s54, 0xffffff80
	ds_read_b128 v[178:181], v145 offset:49152
	ds_read_b128 v[182:185], v145 offset:50176
	ds_read_b128 v[186:189], v145 offset:51200
	ds_read_b128 v[190:193], v145 offset:52224
	ds_read_b128 v[194:197], v145 offset:53248
	ds_read_b128 v[208:211], v145 offset:54272
	ds_read_b128 v[212:215], v145 offset:55296
	ds_read_b128 v[216:219], v145 offset:56320
	global_load_lds_dwordx4 v134, s[40:41] offset:128
	s_add_i32 m0, s54, 0x1f80
	s_nop 0
	global_load_lds_dwordx4 v94, s[40:41] offset:128
	s_add_i32 s54, s53, s6
	s_add_u32 s40, s40, 0x40080
	s_addc_u32 s41, s41, 0
	s_mov_b32 m0, s54
	s_nop 0
	global_load_lds_dwordx4 v134, s[40:41]
	s_add_i32 m0, s54, 0x2000
	s_nop 0
	global_load_lds_dwordx4 v94, s[40:41]
	s_add_u32 s42, s42, 0xfffc0080
	s_addc_u32 s43, s43, -1
	s_mov_b32 m0, s28
	s_nop 0
	global_load_lds_dwordx4 v134, s[42:43]
	s_mov_b32 m0, s29
	s_nop 0
	global_load_lds_dwordx4 v94, s[42:43]
	s_waitcnt vmcnt(8)
	s_waitcnt lgkmcnt(0)
	s_cmp_lg_u32 s51, 12
	s_cbranch_scc1 .Lup_nopf
	s_lshl_b32 s54, s46, 8
	s_add_i32 s54, s54, s25
	v_and_b32_e32 v232, 0x18, v143
	v_or_b32_e32 v233, s54, v97
	v_lshrrev_b32_e32 v232, 1, v232
	v_lshl_add_u32 v232, v233, 4, v232
	global_load_dword v233, v232, s[16:17]
	global_load_dword v234, v232, s[16:17] offset:256
	global_load_dword v235, v232, s[16:17] offset:512
	global_load_dword v236, v232, s[16:17] offset:768
	global_load_dword v237, v232, s[16:17] offset:2048
	global_load_dword v238, v232, s[16:17] offset:2304
	global_load_dword v239, v232, s[16:17] offset:2560
	global_load_dword v240, v232, s[16:17] offset:2816
.Lup_nopf:
	s_barrier
	s_setprio 1
	s_waitcnt lgkmcnt(0)
	v_mfma_f32_16x16x32_bf16 v[62:65], v[146:149], v[178:181], v[62:65]
	v_mfma_f32_16x16x32_bf16 v[58:61], v[154:157], v[178:181], v[58:61]
	v_mfma_f32_16x16x32_bf16 v[46:49], v[146:149], v[186:189], v[46:49]
	v_mfma_f32_16x16x32_bf16 v[42:45], v[154:157], v[186:189], v[42:45]
	v_mfma_f32_16x16x32_bf16 v[30:33], v[146:149], v[194:197], v[30:33]
	v_mfma_f32_16x16x32_bf16 v[26:29], v[154:157], v[194:197], v[26:29]
	v_mfma_f32_16x16x32_bf16 v[14:17], v[146:149], v[212:215], v[14:17]
	v_mfma_f32_16x16x32_bf16 v[10:13], v[154:157], v[212:215], v[10:13]
	v_mfma_f32_16x16x32_bf16 v[62:65], v[150:153], v[182:185], v[62:65]
	v_mfma_f32_16x16x32_bf16 v[58:61], v[158:161], v[182:185], v[58:61]
	v_mfma_f32_16x16x32_bf16 v[46:49], v[150:153], v[190:193], v[46:49]
	v_mfma_f32_16x16x32_bf16 v[42:45], v[158:161], v[190:193], v[42:45]
	v_mfma_f32_16x16x32_bf16 v[30:33], v[150:153], v[208:211], v[30:33]
	v_mfma_f32_16x16x32_bf16 v[26:29], v[158:161], v[208:211], v[26:29]
	v_mfma_f32_16x16x32_bf16 v[14:17], v[150:153], v[216:219], v[14:17]
	v_mfma_f32_16x16x32_bf16 v[10:13], v[158:161], v[216:219], v[10:13]
	v_mfma_f32_16x16x32_bf16 v[54:57], v[162:165], v[178:181], v[54:57]
	v_mfma_f32_16x16x32_bf16 v[50:53], v[170:173], v[178:181], v[50:53]
	v_mfma_f32_16x16x32_bf16 v[38:41], v[162:165], v[186:189], v[38:41]
	v_mfma_f32_16x16x32_bf16 v[34:37], v[170:173], v[186:189], v[34:37]
	v_mfma_f32_16x16x32_bf16 v[22:25], v[162:165], v[194:197], v[22:25]
	v_mfma_f32_16x16x32_bf16 v[18:21], v[170:173], v[194:197], v[18:21]
	v_mfma_f32_16x16x32_bf16 v[6:9], v[162:165], v[212:215], v[6:9]
	v_mfma_f32_16x16x32_bf16 v[2:5], v[170:173], v[212:215], v[2:5]
	v_mfma_f32_16x16x32_bf16 v[54:57], v[166:169], v[182:185], v[54:57]
	v_mfma_f32_16x16x32_bf16 v[50:53], v[174:177], v[182:185], v[50:53]
	v_mfma_f32_16x16x32_bf16 v[38:41], v[166:169], v[190:193], v[38:41]
	v_mfma_f32_16x16x32_bf16 v[34:37], v[174:177], v[190:193], v[34:37]
	v_mfma_f32_16x16x32_bf16 v[22:25], v[166:169], v[208:211], v[22:25]
	v_mfma_f32_16x16x32_bf16 v[18:21], v[174:177], v[208:211], v[18:21]
	v_mfma_f32_16x16x32_bf16 v[6:9], v[166:169], v[216:219], v[6:9]
	v_mfma_f32_16x16x32_bf16 v[2:5], v[174:177], v[216:219], v[2:5]
	s_setprio 0
	s_barrier
	s_add_i32 s51, s51, 2
	s_add_u32 s49, s49, 0x100
	s_addc_u32 s50, s50, 0
	s_add_u32 s38, s38, 0x100
	s_addc_u32 s39, s39, 0
	s_cmp_gt_u32 s51, 13
	s_cbranch_scc0 .LBB0_565
	s_lshl_b32 s19, s46, 8
	s_add_i32 s19, s19, s25
	v_lshl_or_b32 v184, s45, 7, v143
	s_and_b64 vcc, exec, s[10:11]
	s_cbranch_vccz .LBB0_568
	s_barrier
